# non-temporal hint on the write-once/read-once split-K query partials (stores in the xq GEMM epilogue, loads in cross attention)
# baseline (speedup 1.0000x reference)
; __device__ __forceinline__ unsigned cvt_pk_bf16(float lo, float hi) { unsigned r; asm volatile("v_cvt_pk_bf16_f32 %0, %1, %2" : "=v"(r) : "v"(lo), "v"(hi)); return r; }
; #define PG8_BAR __builtin_amdgcn_s_barrier()
;     __device__ __forceinline__ void operator()(const f32x4 (&acc)[2][2][4][2], const Unit& u, int wr, int wc, int fr, int fq) const {
;         const int row0 = u.pm * BM + wr * 64 + fr, col0 = (u.pn & 1) * BM + wc * 32 + 8 * fq;
;         bf16_t* base = Q + (size_t)(u.pn >> 1) * ((size_t)T * 512);
; #pragma unroll
;         for (int ai = 0; ai < 2; ++ai)
; #pragma unroll
;             for (int m = 0; m < 4; ++m) { bf16_t* rowp = base + (size_t)(row0 + ai * HALF + m * 16) * 512 + col0;
; #pragma unroll
;                 for (int bj = 0; bj < 2; ++bj) { const f32x4 v0 = acc[ai][bj][m][0], v1 = acc[ai][bj][m][1];
;                     u32x4 o; o.x = cvt_pk_bf16(v0[0], v0[1]); o.y = cvt_pk_bf16(v0[2], v0[3]); o.z = cvt_pk_bf16(v1[0], v1[1]); o.w = cvt_pk_bf16(v1[2], v1[3]);
;                     *(u32x4*)(rowp + bj * HALF) = o; } }
;     }
; template <class Epi, class Sched, bool ALIGN_EPI = true, bool SP2 = true, bool GS = false>
; __device__ __forceinline__ void gemm_phase(PG8_LAS unsigned char* lds, const Gemm g, const Sched& S, const Epi& E, const float* gs_ss = nullptr) {
;     ...
;         if (!has_next) break;
; #pragma unroll
;         for (int a = 0; a < 2; ++a)
; #pragma unroll
;             for (int b = 0; b < 2; ++b)
; #pragma unroll
;                 for (int m = 0; m < 4; ++m)
; #pragma unroll
;                     for (int n = 0; n < 2; ++n) acc[a][b][m][n] = (f32x4){0.f, 0.f, 0.f, 0.f};
;         cur = nxt; cA = nA; cB = nB; ++ui;
;         if constexpr (GS) { gpar ^= 1; PG8_GS_BUILD(cur, gpar); }
;         if constexpr (ALIGN_EPI) { if (wr == 1) PG8_BAR; }
.LBB0_1122:
	s_lshl_b32 s2, s50, 8
	s_and_b32 s2, s2, 0x100
	v_or_b32_e32 v0, s2, v146
	s_lshl_b32 s2, s50, 22
	s_and_b32 s2, s2, 0x1800000
	v_lshl_add_u32 v148, s51, 8, v144
	s_add_u32 s2, s37, s2
	s_addc_u32 s3, s46, 0
	v_lshlrev_b32_e32 v0, 1, v0
	v_ashrrev_i32_e32 v149, 31, v148
	v_lshl_add_u64 v[150:151], s[2:3], 0, v[0:1]
	v_lshlrev_b64 v[142:143], 10, v[148:149]
	v_lshl_add_u64 v[142:143], v[150:151], 0, v[142:143]
	v_cvt_pk_bf16_f32 v126, v126, v127
	v_cvt_pk_bf16_f32 v127, v128, v129
	v_cvt_pk_bf16_f32 v128, v122, v123
	v_cvt_pk_bf16_f32 v129, v124, v125
	global_store_dwordx4 v[142:143], v[126:129], off nt
	v_cvt_pk_bf16_f32 v114, v114, v115
	v_cvt_pk_bf16_f32 v115, v116, v117
	v_cvt_pk_bf16_f32 v116, v106, v107
	v_or_b32_e32 v106, 16, v148
	v_ashrrev_i32_e32 v107, 31, v106
	v_lshlrev_b64 v[106:107], 10, v[106:107]
	v_cvt_pk_bf16_f32 v117, v108, v109
	global_store_dwordx4 v[142:143], v[114:117], off offset:256 nt
	s_mov_b64 s[2:3], 0x20000
	s_nop 0
	v_lshl_add_u64 v[114:115], v[150:151], 0, v[106:107]
	v_cvt_pk_bf16_f32 v106, v118, v119
	v_cvt_pk_bf16_f32 v107, v120, v121
	v_cvt_pk_bf16_f32 v108, v110, v111
	v_cvt_pk_bf16_f32 v109, v112, v113
	global_store_dwordx4 v[114:115], v[106:109], off nt
	v_cvt_pk_bf16_f32 v98, v98, v99
	v_cvt_pk_bf16_f32 v99, v100, v101
	v_cvt_pk_bf16_f32 v100, v90, v91
	v_or_b32_e32 v90, 32, v148
	v_ashrrev_i32_e32 v91, 31, v90
	v_lshlrev_b64 v[90:91], 10, v[90:91]
	v_cvt_pk_bf16_f32 v101, v92, v93
	global_store_dwordx4 v[114:115], v[98:101], off offset:256 nt
	s_nop 1
	v_lshl_add_u64 v[98:99], v[150:151], 0, v[90:91]
	v_cvt_pk_bf16_f32 v90, v102, v103
	v_cvt_pk_bf16_f32 v91, v104, v105
	v_cvt_pk_bf16_f32 v92, v94, v95
	v_cvt_pk_bf16_f32 v93, v96, v97
	global_store_dwordx4 v[98:99], v[90:93], off nt
	v_cvt_pk_bf16_f32 v82, v82, v83
	v_cvt_pk_bf16_f32 v83, v84, v85
	v_cvt_pk_bf16_f32 v84, v74, v75
	v_or_b32_e32 v74, 48, v148
	v_ashrrev_i32_e32 v75, 31, v74
	v_lshlrev_b64 v[74:75], 10, v[74:75]
	v_cvt_pk_bf16_f32 v85, v76, v77
	global_store_dwordx4 v[98:99], v[82:85], off offset:256 nt
	s_nop 1
	v_lshl_add_u64 v[82:83], v[150:151], 0, v[74:75]
	v_cvt_pk_bf16_f32 v74, v86, v87
	v_cvt_pk_bf16_f32 v75, v88, v89
	v_cvt_pk_bf16_f32 v76, v78, v79
	v_cvt_pk_bf16_f32 v77, v80, v81
	global_store_dwordx4 v[82:83], v[74:77], off nt
	v_cvt_pk_bf16_f32 v70, v70, v71
	v_cvt_pk_bf16_f32 v71, v72, v73
	v_cvt_pk_bf16_f32 v72, v66, v67
	v_lshl_add_u64 v[66:67], v[142:143], 0, s[2:3]
	s_mov_b32 s2, 0x20000
	v_cvt_pk_bf16_f32 v73, v68, v69
	global_store_dwordx4 v[82:83], v[70:73], off offset:256 nt
	v_cvt_pk_bf16_f32 v62, v62, v63
	v_cvt_pk_bf16_f32 v63, v64, v65
	v_cvt_pk_bf16_f32 v64, v58, v59
	v_add_co_u32_e32 v58, vcc, s2, v142
	v_cvt_pk_bf16_f32 v65, v60, v61
	s_mov_b64 s[2:3], 0x24000
	s_nop 0
	v_addc_co_u32_e32 v59, vcc, 0, v143, vcc
	global_store_dwordx4 v[58:59], v[62:65], off nt
	v_cvt_pk_bf16_f32 v50, v50, v51
	v_cvt_pk_bf16_f32 v51, v52, v53
	v_cvt_pk_bf16_f32 v52, v42, v43
	v_cvt_pk_bf16_f32 v53, v44, v45
	global_store_dwordx4 v[66:67], v[50:53], off offset:256 nt
	v_cvt_pk_bf16_f32 v42, v54, v55
	v_cvt_pk_bf16_f32 v43, v56, v57
	v_cvt_pk_bf16_f32 v44, v46, v47
	v_cvt_pk_bf16_f32 v45, v48, v49
	s_nop 1
	v_lshl_add_u64 v[50:51], v[142:143], 0, s[2:3]
	s_mov_b32 s2, 0x24000
	v_add_co_u32_e32 v46, vcc, s2, v142
	s_mov_b64 s[2:3], 0x28000
	s_nop 0
	v_addc_co_u32_e32 v47, vcc, 0, v143, vcc
	global_store_dwordx4 v[46:47], v[42:45], off nt
	v_cvt_pk_bf16_f32 v34, v34, v35
	v_cvt_pk_bf16_f32 v35, v36, v37
	v_cvt_pk_bf16_f32 v36, v26, v27
	v_cvt_pk_bf16_f32 v37, v28, v29
	global_store_dwordx4 v[50:51], v[34:37], off offset:256 nt
	v_cvt_pk_bf16_f32 v26, v38, v39
	v_cvt_pk_bf16_f32 v27, v40, v41
	v_cvt_pk_bf16_f32 v28, v30, v31
	v_cvt_pk_bf16_f32 v29, v32, v33
	s_nop 1
	v_lshl_add_u64 v[34:35], v[142:143], 0, s[2:3]
	s_mov_b32 s2, 0x28000
	v_add_co_u32_e32 v30, vcc, s2, v142
	s_mov_b64 s[2:3], 0x2c000
	s_nop 0
	v_addc_co_u32_e32 v31, vcc, 0, v143, vcc
	global_store_dwordx4 v[30:31], v[26:29], off nt
	v_cvt_pk_bf16_f32 v18, v18, v19
	v_cvt_pk_bf16_f32 v19, v20, v21
	v_cvt_pk_bf16_f32 v20, v10, v11
	v_cvt_pk_bf16_f32 v21, v12, v13
	global_store_dwordx4 v[34:35], v[18:21], off offset:256 nt
	v_cvt_pk_bf16_f32 v10, v22, v23
	v_cvt_pk_bf16_f32 v11, v24, v25
	v_cvt_pk_bf16_f32 v12, v14, v15
	v_cvt_pk_bf16_f32 v13, v16, v17
	s_nop 1
	v_lshl_add_u64 v[18:19], v[142:143], 0, s[2:3]
	s_mov_b32 s2, 0x2c000
	v_add_co_u32_e32 v14, vcc, s2, v142
	s_mov_b64 s[2:3], -1
	s_nop 0
	v_addc_co_u32_e32 v15, vcc, 0, v143, vcc
	s_andn2_b64 vcc, exec, s[42:43]
	global_store_dwordx4 v[14:15], v[10:13], off nt
	v_cvt_pk_bf16_f32 v6, v6, v7
	v_cvt_pk_bf16_f32 v7, v8, v9
	v_cvt_pk_bf16_f32 v8, v2, v3
	v_cvt_pk_bf16_f32 v9, v4, v5
	global_store_dwordx4 v[18:19], v[6:9], off offset:256 nt
	s_cbranch_vccnz .LBB0_1117
	s_andn2_b64 vcc, exec, s[34:35]
	s_cbranch_vccnz .LBB0_1116
	s_barrier
	s_branch .LBB0_1116

; __device__ __forceinline__ int tid_fresh() { int t = threadIdx.x; asm volatile("" : "+v"(t)); return t; }
; __device__ __forceinline__ unsigned pk2(float lo, float hi) { const hf32x2 v = {lo, hi}; return __builtin_bit_cast(unsigned, __builtin_convertvector(v, hbf16x2)); }
; __device__ __forceinline__ void cross_attn_unit(PP p, unsigned char* shm, int u, int l) {
;     const bf16_t* kvb = (const bf16_t*)(p->ws + WS_KV);
;     bf16_t* Ks = (bf16_t*)(shm + AT_KS); bf16_t* Vt = (bf16_t*)(shm + AT_VT);
;     const int tid = tid_fresh(), w = tid >> 6, lane = tid & 63, fr = lane & 15, quad = lane >> 4;
;     const int b = u / 64, xh = (u / 16) % 4, qt = u % 16;
;     const size_t rowq = (size_t)(b * SEQ + qt * 128 + 16 * w + fr);
;     float qs;
;     { const float* sp = (const float*)(p->ws + WS_SS) + ((size_t)(1 + 3 * l) * T + rowq) * 32 + quad * 8;
;       const f32x4 a0 = *(const f32x4*)sp, a1 = *(const f32x4*)(sp + 4);
;       float t = ((a0[0] + a0[1]) + (a0[2] + a0[3])) + ((a1[0] + a1[1]) + (a1[2] + a1[3]));
;       t += __shfl_xor(t, 16); t += __shfl_xor(t, 32);
;       qs = (0.08838834764831845f * 1.4426950408889634f) / sqrtf(t * (1.0f / D) + EPS); }
;     bf16x8 qf[4];
;     const bf16_t* qp = (const bf16_t*)(p->ws + WS_QP) + rowq * 512 + xh * 128 + quad * 8;
; #pragma unroll
;     for (int ks = 0; ks < 4; ++ks) {
;         float acc8[8], t8[8];
;         unpack8(*(const u32x4*)(qp + 32 * ks), acc8);
; #pragma unroll
;         for (int sp = 1; sp < 4; ++sp) { unpack8(*(const u32x4*)(qp + (size_t)sp * T * 512 + 32 * ks), t8);
; #pragma unroll
;             for (int e = 0; e < 8; ++e) acc8[e] += t8[e]; }
;         u32x4 pk; pk.x = pk2(acc8[0] * qs, acc8[1] * qs); pk.y = pk2(acc8[2] * qs, acc8[3] * qs); pk.z = pk2(acc8[4] * qs, acc8[5] * qs); pk.w = pk2(acc8[6] * qs, acc8[7] * qs);
;         qf[ks] = __builtin_bit_cast(bf16x8, pk);
;     }
.LBB0_1180:
	s_ashr_i32 s12, s2, 31
	s_lshr_b32 s13, s12, 26
	s_lshr_b32 s12, s12, 28
	s_mov_b64 s[8:9], s[0:1]
	s_add_i32 s13, s2, s13
	s_add_i32 s12, s2, s12
	v_mov_b32_e32 v21, v222
	s_ashr_i32 s17, s13, 6
	s_ashr_i32 s13, s12, 4
	s_load_dwordx2 s[8:9], s[8:9], 0x110
	s_lshr_b32 s12, s13, 30
	v_ashrrev_i32_e32 v0, 2, v21
	s_add_i32 s12, s13, s12
	v_and_b32_e32 v0, -16, v0
	v_and_b32_e32 v24, 15, v21
	s_and_b32 s12, s12, 0x1fffffc
	v_lshl_add_u32 v0, s17, 11, v0
	s_sub_i32 s12, s13, s12
	v_or_b32_e32 v0, v0, v24
	s_lshl_b32 s13, s13, 11
	v_subrev_u32_e32 v0, s13, v0
	v_add_u32_e32 v2, s3, v0
	s_mul_i32 s13, s28, 0x300000
	v_ashrrev_i32_e32 v3, 31, v2
	s_waitcnt lgkmcnt(0)
	s_add_u32 s20, s8, s13
	v_bfe_u32 v14, v21, 4, 2
	s_addc_u32 s21, s9, 0
	v_lshlrev_b64 v[4:5], 7, v[2:3]
	v_lshl_add_u64 v[4:5], s[20:21], 0, v[4:5]
	v_lshlrev_b32_e32 v6, 5, v14
	v_mov_b32_e32 v7, v1
	v_lshl_add_u64 v[4:5], v[4:5], 0, v[6:7]
	s_mov_b64 s[20:21], 0x35dc4000
	s_mov_b32 s13, 0x35dc4000
	v_lshl_add_u64 v[8:9], v[4:5], 0, s[20:21]
	v_add_co_u32_e32 v4, vcc, s13, v4
	s_lshl_b32 s12, s12, 7
	s_nop 0
	v_addc_co_u32_e32 v5, vcc, 0, v5, vcc
	global_load_dwordx4 v[4:7], v[4:5], off
	s_nop 0
	global_load_dwordx4 v[8:11], v[8:9], off offset:16
	v_lshlrev_b64 v[2:3], 10, v[2:3]
	s_ashr_i32 s13, s12, 31
	s_lshl_b64 s[12:13], s[12:13], 1
	v_lshl_add_u64 v[2:3], s[8:9], 0, v[2:3]
	v_lshlrev_b32_e32 v18, 4, v14
	v_mov_b32_e32 v19, v1
	v_lshl_add_u64 v[36:37], v[2:3], 0, s[12:13]
	v_lshlrev_b32_e32 v0, 3, v14
	v_lshl_add_u64 v[14:15], v[36:37], 0, v[18:19]
	s_mov_b32 s18, 0x369c4000
	s_add_u32 s8, s8, s16
	s_addc_u32 s9, s9, 0
	s_add_u32 s8, s8, s12
	s_addc_u32 s9, s9, s13
	v_lshl_add_u64 v[36:37], v[36:37], 0, v[0:1]
	s_add_i32 s2, s2, s66
	s_add_i32 s3, s3, s14
	s_waitcnt vmcnt(1)
	v_mov_b32_e32 v12, v4
	s_waitcnt vmcnt(0)
	v_mov_b32_e32 v13, v8
	v_mov_b32_e32 v8, v5
	v_pk_add_f32 v[4:5], v[12:13], v[8:9]
	v_mov_b32_e32 v8, v6
	v_mov_b32_e32 v9, v10
	v_mov_b32_e32 v10, v7
	v_pk_add_f32 v[6:7], v[8:9], v[10:11]
	s_nop 0
	v_pk_add_f32 v[4:5], v[4:5], v[6:7]
	v_and_b32_e32 v6, 64, v226
	v_add_f32_e32 v4, v4, v5
	v_xor_b32_e32 v5, 16, v226
	v_add_u32_e32 v6, 64, v6
	v_cmp_lt_i32_e32 vcc, v5, v6
	s_nop 1
	v_cndmask_b32_e32 v5, v226, v5, vcc
	v_lshlrev_b32_e32 v25, 2, v5
	ds_bpermute_b32 v5, v25, v4
	s_waitcnt lgkmcnt(0)
	v_add_f32_e32 v4, v4, v5
	v_xor_b32_e32 v5, 32, v226
	v_cmp_lt_i32_e32 vcc, v5, v6
	s_nop 1
	v_cndmask_b32_e32 v5, v226, v5, vcc
	v_lshlrev_b32_e32 v34, 2, v5
	ds_bpermute_b32 v5, v34, v4
	s_waitcnt lgkmcnt(0)
	v_add_f32_e32 v4, v4, v5
	v_fmamk_f32 v4, v4, 0x3a000000, v223
	v_cmp_gt_f32_e32 vcc, s11, v4
	v_mul_f32_e32 v5, 0x4f800000, v4
	s_nop 0
	v_cndmask_b32_e32 v4, v4, v5, vcc
	v_sqrt_f32_e32 v5, v4
	s_nop 0
	v_add_u32_e32 v6, -1, v5
	v_fma_f32 v7, -v6, v5, v4
	v_cmp_ge_f32_e64 s[38:39], 0, v7
	v_add_u32_e32 v7, 1, v5
	s_nop 0
	v_cndmask_b32_e64 v6, v5, v6, s[38:39]
	v_fma_f32 v5, -v7, v5, v4
	v_cmp_lt_f32_e64 s[38:39], 0, v5
	s_nop 1
	v_cndmask_b32_e64 v5, v6, v7, s[38:39]
	v_mul_f32_e32 v6, 0x37800000, v5
	v_cndmask_b32_e32 v5, v5, v6, vcc
	v_cmp_class_f32_e32 vcc, v4, v224
	s_nop 1
	v_cndmask_b32_e32 v4, v5, v4, vcc
	v_div_scale_f32 v5, s[20:21], v4, v4, s23
	v_rcp_f32_e32 v6, v5
	s_mov_b64 s[20:21], 0x369c4000
	v_lshl_add_u64 v[22:23], v[14:15], 0, s[20:21]
	v_fma_f32 v7, -v5, v6, 1.0
	v_fmac_f32_e32 v6, v7, v6
	v_div_scale_f32 v7, vcc, s23, v4, s23
	v_mul_f32_e32 v8, v7, v6
	v_fma_f32 v9, -v5, v8, v7
	v_fmac_f32_e32 v8, v9, v6
	v_fma_f32 v5, -v5, v8, v7
	v_div_fmas_f32 v5, v5, v6, v8
	v_add_co_u32_e32 v2, vcc, s18, v14
	s_mov_b32 s18, 0x371c4000
	s_nop 0
	v_addc_co_u32_e32 v3, vcc, 0, v15, vcc
	v_add_co_u32_e32 v38, vcc, s18, v14
	s_mov_b32 s18, 0x379c4000
	s_nop 0
	v_addc_co_u32_e32 v39, vcc, 0, v15, vcc
	v_add_co_u32_e32 v40, vcc, s18, v14
	s_mov_b32 s18, 0x381c4000
	s_nop 0
	v_addc_co_u32_e32 v41, vcc, 0, v15, vcc
	v_div_fixup_f32 v20, v5, v4, s23
	global_load_dwordx4 v[2:5], v[2:3], off nt
	v_add_co_u32_e32 v42, vcc, s18, v14
	global_load_dwordx4 v[6:9], v[38:39], off nt
	global_load_dwordx4 v[10:13], v[40:41], off nt
	v_addc_co_u32_e32 v43, vcc, 0, v15, vcc
	global_load_dwordx4 v[14:17], v[42:43], off nt
	global_load_dwordx4 v[130:133], v[22:23], off offset:64 nt
	global_load_dwordx4 v[134:137], v[38:39], off offset:64 nt
	global_load_dwordx4 v[138:141], v[40:41], off offset:64 nt
	global_load_dwordx4 v[142:145], v[42:43], off offset:64 nt
	global_load_dwordx4 v[146:149], v[22:23], off offset:128 nt
	global_load_dwordx4 v[150:153], v[38:39], off offset:128 nt
	global_load_dwordx4 v[154:157], v[40:41], off offset:128 nt
	global_load_dwordx4 v[158:161], v[42:43], off offset:128 nt
	global_load_dwordx4 v[162:165], v[22:23], off offset:192 nt
	global_load_dwordx4 v[166:169], v[38:39], off offset:192 nt
	global_load_dwordx4 v[170:173], v[40:41], off offset:192 nt
	global_load_dwordx4 v[174:177], v[42:43], off offset:192 nt
	s_waitcnt vmcnt(15)
	v_lshlrev_b32_e32 v26, 16, v2
	v_and_b32_e32 v27, 0xffff0000, v2
	s_waitcnt vmcnt(14)
	v_lshlrev_b32_e32 v28, 16, v6
	v_and_b32_e32 v29, 0xffff0000, v6
	v_pk_add_f32 v[26:27], v[26:27], v[28:29]
	s_waitcnt vmcnt(13)
	v_lshlrev_b32_e32 v28, 16, v10
	v_and_b32_e32 v29, 0xffff0000, v10
	v_pk_add_f32 v[26:27], v[26:27], v[28:29]
	s_waitcnt vmcnt(12)
; __device__ __forceinline__ unsigned pk2(float lo, float hi) { const hf32x2 v = {lo, hi}; return __builtin_bit_cast(unsigned, __builtin_convertvector(v, hbf16x2)); }
; __device__ __forceinline__ void cross_attn_unit(PP p, unsigned char* shm, int u, int l) {
;     ...
; #pragma unroll
;     for (int ks = 0; ks < 4; ++ks) {
;         float acc8[8], t8[8];
;         unpack8(*(const u32x4*)(qp + 32 * ks), acc8);
; #pragma unroll
;         for (int sp = 1; sp < 4; ++sp) { unpack8(*(const u32x4*)(qp + (size_t)sp * T * 512 + 32 * ks), t8);
; #pragma unroll
;             for (int e = 0; e < 8; ++e) acc8[e] += t8[e]; }
;         u32x4 pk; pk.x = pk2(acc8[0] * qs, acc8[1] * qs); pk.y = pk2(acc8[2] * qs, acc8[3] * qs); pk.z = pk2(acc8[4] * qs, acc8[5] * qs); pk.w = pk2(acc8[6] * qs, acc8[7] * qs);
;         qf[ks] = __builtin_bit_cast(bf16x8, pk);
;     }
	v_lshlrev_b32_e32 v28, 16, v14
	v_and_b32_e32 v29, 0xffff0000, v14
	v_pk_add_f32 v[26:27], v[26:27], v[28:29]
	v_lshlrev_b32_e32 v6, 16, v7
	v_pk_mul_f32 v[26:27], v[20:21], v[26:27] op_sel_hi:[0,1]
	v_cvt_pk_bf16_f32 v2, v26, v27
	v_lshlrev_b32_e32 v26, 16, v3
	v_and_b32_e32 v27, 0xffff0000, v3
	v_and_b32_e32 v7, 0xffff0000, v7
	v_pk_add_f32 v[6:7], v[26:27], v[6:7]
	v_lshlrev_b32_e32 v10, 16, v11
	v_and_b32_e32 v11, 0xffff0000, v11
	v_pk_add_f32 v[6:7], v[6:7], v[10:11]
	v_lshlrev_b32_e32 v10, 16, v15
	v_and_b32_e32 v11, 0xffff0000, v15
	v_pk_add_f32 v[6:7], v[6:7], v[10:11]
	v_lshlrev_b32_e32 v10, 16, v8
	v_pk_mul_f32 v[6:7], v[20:21], v[6:7] op_sel_hi:[0,1]
	v_cvt_pk_bf16_f32 v3, v6, v7
	v_lshlrev_b32_e32 v6, 16, v4
	v_and_b32_e32 v7, 0xffff0000, v4
	v_and_b32_e32 v11, 0xffff0000, v8
	v_pk_add_f32 v[6:7], v[6:7], v[10:11]
	v_lshlrev_b32_e32 v10, 16, v12
	v_and_b32_e32 v11, 0xffff0000, v12
	v_pk_add_f32 v[6:7], v[6:7], v[10:11]
	v_lshlrev_b32_e32 v10, 16, v16
	v_and_b32_e32 v11, 0xffff0000, v16
	v_pk_add_f32 v[6:7], v[6:7], v[10:11]
	v_lshlrev_b32_e32 v8, 16, v9
	v_pk_mul_f32 v[6:7], v[20:21], v[6:7] op_sel_hi:[0,1]
	v_cvt_pk_bf16_f32 v4, v6, v7
	v_lshlrev_b32_e32 v6, 16, v5
	v_and_b32_e32 v7, 0xffff0000, v5
	v_and_b32_e32 v9, 0xffff0000, v9
	v_pk_add_f32 v[6:7], v[6:7], v[8:9]
	v_lshlrev_b32_e32 v8, 16, v13
	v_and_b32_e32 v9, 0xffff0000, v13
	v_pk_add_f32 v[6:7], v[6:7], v[8:9]
	v_lshlrev_b32_e32 v8, 16, v17
	v_and_b32_e32 v9, 0xffff0000, v17
	v_pk_add_f32 v[6:7], v[6:7], v[8:9]
	s_nop 0
	v_pk_mul_f32 v[6:7], v[20:21], v[6:7] op_sel_hi:[0,1]
	v_cvt_pk_bf16_f32 v5, v6, v7
	s_waitcnt vmcnt(8)
	v_mov_b32_e32 v6, v130
	v_mov_b32_e32 v7, v131
	v_mov_b32_e32 v8, v132
	v_mov_b32_e32 v9, v133
	v_mov_b32_e32 v10, v134
	v_mov_b32_e32 v11, v135
	v_mov_b32_e32 v12, v136
	v_mov_b32_e32 v13, v137
	v_mov_b32_e32 v14, v138
	v_mov_b32_e32 v15, v139
	v_mov_b32_e32 v16, v140
	v_mov_b32_e32 v17, v141
	v_mov_b32_e32 v26, v142
	v_mov_b32_e32 v27, v143
	v_mov_b32_e32 v28, v144
	v_mov_b32_e32 v29, v145
	v_lshlrev_b32_e32 v30, 16, v6
	v_and_b32_e32 v31, 0xffff0000, v6
	v_lshlrev_b32_e32 v32, 16, v10
	v_and_b32_e32 v33, 0xffff0000, v10
	v_pk_add_f32 v[30:31], v[30:31], v[32:33]
	v_lshlrev_b32_e32 v32, 16, v14
	v_and_b32_e32 v33, 0xffff0000, v14
	v_pk_add_f32 v[30:31], v[30:31], v[32:33]
	v_lshlrev_b32_e32 v32, 16, v26
	v_and_b32_e32 v33, 0xffff0000, v26
	v_pk_add_f32 v[30:31], v[30:31], v[32:33]
	v_lshlrev_b32_e32 v10, 16, v11
	v_pk_mul_f32 v[30:31], v[20:21], v[30:31] op_sel_hi:[0,1]
	v_cvt_pk_bf16_f32 v6, v30, v31
	v_lshlrev_b32_e32 v30, 16, v7
	v_and_b32_e32 v31, 0xffff0000, v7
	v_and_b32_e32 v11, 0xffff0000, v11
	v_pk_add_f32 v[10:11], v[30:31], v[10:11]
	v_lshlrev_b32_e32 v14, 16, v15
	v_and_b32_e32 v15, 0xffff0000, v15
	v_pk_add_f32 v[10:11], v[10:11], v[14:15]
	v_lshlrev_b32_e32 v14, 16, v27
	v_and_b32_e32 v15, 0xffff0000, v27
	v_pk_add_f32 v[10:11], v[10:11], v[14:15]
	v_lshlrev_b32_e32 v14, 16, v12
	v_pk_mul_f32 v[10:11], v[20:21], v[10:11] op_sel_hi:[0,1]
	v_cvt_pk_bf16_f32 v7, v10, v11
	v_lshlrev_b32_e32 v10, 16, v8
	v_and_b32_e32 v11, 0xffff0000, v8
	v_and_b32_e32 v15, 0xffff0000, v12
	v_pk_add_f32 v[10:11], v[10:11], v[14:15]
	v_lshlrev_b32_e32 v14, 16, v16
	v_and_b32_e32 v15, 0xffff0000, v16
	v_pk_add_f32 v[10:11], v[10:11], v[14:15]
	v_lshlrev_b32_e32 v14, 16, v28
	v_and_b32_e32 v15, 0xffff0000, v28
	v_pk_add_f32 v[10:11], v[10:11], v[14:15]
	v_lshlrev_b32_e32 v12, 16, v13
	v_pk_mul_f32 v[10:11], v[20:21], v[10:11] op_sel_hi:[0,1]
	v_cvt_pk_bf16_f32 v8, v10, v11
	v_lshlrev_b32_e32 v10, 16, v9
	v_and_b32_e32 v11, 0xffff0000, v9
	v_and_b32_e32 v13, 0xffff0000, v13
	v_pk_add_f32 v[10:11], v[10:11], v[12:13]
	v_lshlrev_b32_e32 v12, 16, v17
	v_and_b32_e32 v13, 0xffff0000, v17
	v_pk_add_f32 v[10:11], v[10:11], v[12:13]
	v_lshlrev_b32_e32 v12, 16, v29
	v_and_b32_e32 v13, 0xffff0000, v29
	v_pk_add_f32 v[10:11], v[10:11], v[12:13]
	s_nop 0
	v_pk_mul_f32 v[10:11], v[20:21], v[10:11] op_sel_hi:[0,1]
	v_cvt_pk_bf16_f32 v9, v10, v11
	s_waitcnt vmcnt(4)
	v_mov_b32_e32 v10, v146
	v_mov_b32_e32 v11, v147
	v_mov_b32_e32 v12, v148
	v_mov_b32_e32 v13, v149
	v_mov_b32_e32 v14, v150
	v_mov_b32_e32 v15, v151
	v_mov_b32_e32 v16, v152
	v_mov_b32_e32 v17, v153
	v_mov_b32_e32 v26, v154
	v_mov_b32_e32 v27, v155
	v_mov_b32_e32 v28, v156
	v_mov_b32_e32 v29, v157
	v_mov_b32_e32 v30, v158
	v_mov_b32_e32 v31, v159
	v_mov_b32_e32 v32, v160
	v_mov_b32_e32 v33, v161
	v_lshlrev_b32_e32 v44, 16, v10
	v_and_b32_e32 v45, 0xffff0000, v10
	v_lshlrev_b32_e32 v46, 16, v14
	v_and_b32_e32 v47, 0xffff0000, v14
	v_pk_add_f32 v[44:45], v[44:45], v[46:47]
	v_lshlrev_b32_e32 v46, 16, v26
	v_and_b32_e32 v47, 0xffff0000, v26
	v_pk_add_f32 v[44:45], v[44:45], v[46:47]
	v_lshlrev_b32_e32 v46, 16, v30
	v_and_b32_e32 v47, 0xffff0000, v30
	v_pk_add_f32 v[44:45], v[44:45], v[46:47]
	v_lshlrev_b32_e32 v14, 16, v15
	v_pk_mul_f32 v[44:45], v[20:21], v[44:45] op_sel_hi:[0,1]
	v_cvt_pk_bf16_f32 v10, v44, v45
	v_lshlrev_b32_e32 v44, 16, v11
	v_and_b32_e32 v45, 0xffff0000, v11
	v_and_b32_e32 v15, 0xffff0000, v15
	v_pk_add_f32 v[14:15], v[44:45], v[14:15]
	v_lshlrev_b32_e32 v26, 16, v27
	v_and_b32_e32 v27, 0xffff0000, v27
	v_pk_add_f32 v[14:15], v[14:15], v[26:27]
	v_lshlrev_b32_e32 v26, 16, v31
	v_and_b32_e32 v27, 0xffff0000, v31
	v_pk_add_f32 v[14:15], v[14:15], v[26:27]
	v_lshlrev_b32_e32 v26, 16, v16
	v_pk_mul_f32 v[14:15], v[20:21], v[14:15] op_sel_hi:[0,1]
	v_cvt_pk_bf16_f32 v11, v14, v15
	v_lshlrev_b32_e32 v14, 16, v12
	v_and_b32_e32 v15, 0xffff0000, v12
	v_and_b32_e32 v27, 0xffff0000, v16
	v_pk_add_f32 v[14:15], v[14:15], v[26:27]
	v_lshlrev_b32_e32 v26, 16, v28
	v_and_b32_e32 v27, 0xffff0000, v28
	v_pk_add_f32 v[14:15], v[14:15], v[26:27]
	v_lshlrev_b32_e32 v26, 16, v32
	v_and_b32_e32 v27, 0xffff0000, v32
	v_pk_add_f32 v[14:15], v[14:15], v[26:27]
	v_lshlrev_b32_e32 v16, 16, v17
	v_pk_mul_f32 v[14:15], v[20:21], v[14:15] op_sel_hi:[0,1]
	v_cvt_pk_bf16_f32 v12, v14, v15
	v_lshlrev_b32_e32 v14, 16, v13
	v_and_b32_e32 v15, 0xffff0000, v13
	v_and_b32_e32 v17, 0xffff0000, v17
	v_pk_add_f32 v[14:15], v[14:15], v[16:17]
	v_lshlrev_b32_e32 v16, 16, v29
	v_and_b32_e32 v17, 0xffff0000, v29
	v_pk_add_f32 v[14:15], v[14:15], v[16:17]
	v_lshlrev_b32_e32 v16, 16, v33
	v_and_b32_e32 v17, 0xffff0000, v33
	v_pk_add_f32 v[14:15], v[14:15], v[16:17]
	s_nop 0
	v_pk_mul_f32 v[14:15], v[20:21], v[14:15] op_sel_hi:[0,1]
	v_cvt_pk_bf16_f32 v13, v14, v15
	s_waitcnt vmcnt(0)
; __device__ __forceinline__ unsigned pk2(float lo, float hi) { const hf32x2 v = {lo, hi}; return __builtin_bit_cast(unsigned, __builtin_convertvector(v, hbf16x2)); }
; __device__ __forceinline__ void cross_attn_unit(PP p, unsigned char* shm, int u, int l) {
;     ...
;     for (int ks = 0; ks < 4; ++ks) {
;         float acc8[8], t8[8];
;         unpack8(*(const u32x4*)(qp + 32 * ks), acc8);
; #pragma unroll
;         for (int sp = 1; sp < 4; ++sp) { unpack8(*(const u32x4*)(qp + (size_t)sp * T * 512 + 32 * ks), t8);
; #pragma unroll
;             for (int e = 0; e < 8; ++e) acc8[e] += t8[e]; }
;         u32x4 pk; pk.x = pk2(acc8[0] * qs, acc8[1] * qs); pk.y = pk2(acc8[2] * qs, acc8[3] * qs); pk.z = pk2(acc8[4] * qs, acc8[5] * qs); pk.w = pk2(acc8[6] * qs, acc8[7] * qs);
;         qf[ks] = __builtin_bit_cast(bf16x8, pk);
;     }
;     {
;         u32x4 kq[8], vq[8];
; #pragma unroll
;         for (int i = 0; i < 8; ++i) { const int m = 2 * (tid >> 4) + (i & 1) + 64 * (i >> 1), ch = tid & 15;
;             const bf16_t* rowp = kvb + (size_t)(b * 256 + m) * 4096 + l * 1024 + xh * 128 + ch * 8; kq[i] = *(const u32x4*)rowp; vq[i] = *(const u32x4*)(rowp + 512); }
; #pragma unroll
;         for (int i = 0; i < 8; ++i) { const int m = 2 * (tid >> 4) + (i & 1) + 64 * (i >> 1), ch = tid & 15; *(u32x4*)(Ks + m * 136 + ch * 8) = kq[i]; }
	v_mov_b32_e32 v14, v162
	v_mov_b32_e32 v15, v163
	v_mov_b32_e32 v16, v164
	v_mov_b32_e32 v17, v165
	v_mov_b32_e32 v26, v166
	v_mov_b32_e32 v27, v167
	v_mov_b32_e32 v28, v168
	v_mov_b32_e32 v29, v169
	v_mov_b32_e32 v30, v170
	v_mov_b32_e32 v31, v171
	v_mov_b32_e32 v32, v172
	v_mov_b32_e32 v33, v173
	v_mov_b32_e32 v38, v174
	v_mov_b32_e32 v39, v175
	v_mov_b32_e32 v40, v176
	v_mov_b32_e32 v41, v177
	s_nop 0
	v_lshlrev_b32_e32 v22, 16, v14
	v_and_b32_e32 v23, 0xffff0000, v14
	v_lshlrev_b32_e32 v42, 16, v26
	v_and_b32_e32 v43, 0xffff0000, v26
	v_pk_add_f32 v[22:23], v[22:23], v[42:43]
	v_lshlrev_b32_e32 v42, 16, v30
	v_and_b32_e32 v43, 0xffff0000, v30
	v_pk_add_f32 v[22:23], v[22:23], v[42:43]
	v_lshlrev_b32_e32 v42, 16, v38
	v_and_b32_e32 v43, 0xffff0000, v38
	v_pk_add_f32 v[22:23], v[22:23], v[42:43]
	v_lshlrev_b32_e32 v26, 16, v27
	v_pk_mul_f32 v[22:23], v[20:21], v[22:23] op_sel_hi:[0,1]
	v_cvt_pk_bf16_f32 v14, v22, v23
	v_lshlrev_b32_e32 v22, 16, v15
	v_and_b32_e32 v23, 0xffff0000, v15
	v_and_b32_e32 v27, 0xffff0000, v27
	v_pk_add_f32 v[22:23], v[22:23], v[26:27]
	v_lshlrev_b32_e32 v26, 16, v31
	v_and_b32_e32 v27, 0xffff0000, v31
	v_pk_add_f32 v[22:23], v[22:23], v[26:27]
	v_lshlrev_b32_e32 v26, 16, v39
	v_and_b32_e32 v27, 0xffff0000, v39
	v_pk_add_f32 v[22:23], v[22:23], v[26:27]
	v_lshlrev_b32_e32 v26, 16, v28
	v_pk_mul_f32 v[22:23], v[20:21], v[22:23] op_sel_hi:[0,1]
	v_cvt_pk_bf16_f32 v15, v22, v23
	v_lshlrev_b32_e32 v22, 16, v16
	v_and_b32_e32 v23, 0xffff0000, v16
	v_and_b32_e32 v27, 0xffff0000, v28
	v_pk_add_f32 v[22:23], v[22:23], v[26:27]
	v_lshlrev_b32_e32 v26, 16, v32
	v_and_b32_e32 v27, 0xffff0000, v32
	v_pk_add_f32 v[22:23], v[22:23], v[26:27]
	v_lshlrev_b32_e32 v26, 16, v40
	v_and_b32_e32 v27, 0xffff0000, v40
	v_pk_add_f32 v[22:23], v[22:23], v[26:27]
	v_lshlrev_b32_e32 v26, 16, v29
	v_pk_mul_f32 v[22:23], v[20:21], v[22:23] op_sel_hi:[0,1]
	v_cvt_pk_bf16_f32 v16, v22, v23
	v_lshlrev_b32_e32 v22, 16, v17
	v_and_b32_e32 v23, 0xffff0000, v17
	v_and_b32_e32 v27, 0xffff0000, v29
	v_pk_add_f32 v[22:23], v[22:23], v[26:27]
	v_lshlrev_b32_e32 v26, 16, v33
	v_and_b32_e32 v27, 0xffff0000, v33
	v_pk_add_f32 v[22:23], v[22:23], v[26:27]
	v_lshlrev_b32_e32 v26, 16, v41
	v_and_b32_e32 v27, 0xffff0000, v41
	v_pk_add_f32 v[22:23], v[22:23], v[26:27]
	v_ashrrev_i32_e32 v27, 3, v21
	v_pk_mul_f32 v[22:23], v[20:21], v[22:23] op_sel_hi:[0,1]
	v_lshlrev_b32_e32 v21, 3, v21
	v_and_b32_e32 v19, -2, v27
	v_and_b32_e32 v26, 0x78, v21
	v_cvt_pk_bf16_f32 v17, v22, v23
	v_lshl_add_u32 v20, s17, 8, v19
	v_lshlrev_b32_e32 v22, 1, v26
	v_mov_b32_e32 v23, v1
	v_lshl_add_u64 v[28:29], s[8:9], 0, v[22:23]
	s_mov_b64 s[8:9], 0x28ec0000
	v_ashrrev_i32_e32 v21, 31, v20
	v_lshl_add_u64 v[32:33], v[28:29], 0, s[8:9]
	v_lshlrev_b64 v[28:29], 13, v[20:21]
	v_or_b32_e32 v42, 1, v20
	v_add_u32_e32 v50, 64, v20
	v_add_u32_e32 v58, 0x41, v20
	v_add_u32_e32 v66, 0x80, v20
	v_add_u32_e32 v74, 0x81, v20
	v_add_u32_e32 v82, 0xc0, v20
	v_add_u32_e32 v20, 0xc1, v20
	v_ashrrev_i32_e32 v43, 31, v42
	v_ashrrev_i32_e32 v51, 31, v50
	v_ashrrev_i32_e32 v59, 31, v58
	v_ashrrev_i32_e32 v67, 31, v66
	v_ashrrev_i32_e32 v75, 31, v74
	v_ashrrev_i32_e32 v83, 31, v82
	v_ashrrev_i32_e32 v21, 31, v20
	v_lshlrev_b64 v[42:43], 13, v[42:43]
	v_lshlrev_b64 v[50:51], 13, v[50:51]
	v_lshlrev_b64 v[58:59], 13, v[58:59]
	v_lshlrev_b64 v[66:67], 13, v[66:67]
	v_lshlrev_b64 v[74:75], 13, v[74:75]
	v_lshlrev_b64 v[82:83], 13, v[82:83]
	v_lshlrev_b64 v[20:21], 13, v[20:21]
	v_lshl_add_u64 v[38:39], v[32:33], 0, v[28:29]
	v_lshl_add_u64 v[46:47], v[32:33], 0, v[42:43]
	v_lshl_add_u64 v[54:55], v[32:33], 0, v[50:51]
	v_lshl_add_u64 v[62:63], v[32:33], 0, v[58:59]
	v_lshl_add_u64 v[70:71], v[32:33], 0, v[66:67]
	v_lshl_add_u64 v[78:79], v[32:33], 0, v[74:75]
	v_lshl_add_u64 v[86:87], v[32:33], 0, v[82:83]
	v_lshl_add_u64 v[20:21], v[32:33], 0, v[20:21]
	global_load_dwordx4 v[28:31], v[38:39], off
	s_nop 0
	global_load_dwordx4 v[38:41], v[38:39], off offset:1024
	s_nop 0
	global_load_dwordx4 v[42:45], v[46:47], off
	s_nop 0
	global_load_dwordx4 v[46:49], v[46:47], off offset:1024
	s_nop 0
	global_load_dwordx4 v[50:53], v[54:55], off
	s_nop 0
	global_load_dwordx4 v[54:57], v[54:55], off offset:1024
	s_nop 0
	global_load_dwordx4 v[58:61], v[62:63], off
	s_nop 0
	global_load_dwordx4 v[62:65], v[62:63], off offset:1024
	s_nop 0
	global_load_dwordx4 v[66:69], v[70:71], off
	s_nop 0
	global_load_dwordx4 v[70:73], v[70:71], off offset:1024
	s_nop 0
	global_load_dwordx4 v[74:77], v[78:79], off
	s_nop 0
	global_load_dwordx4 v[78:81], v[78:79], off offset:1024
	s_nop 0
	global_load_dwordx4 v[82:85], v[86:87], off
	s_nop 0
	global_load_dwordx4 v[86:89], v[86:87], off offset:1024
	s_nop 0
	global_load_dwordx4 v[90:93], v[20:21], off
	global_load_dwordx4 v[94:97], v[20:21], off offset:1024
	v_add_u32_e32 v20, 0, v22
	v_mad_u64_u32 v[22:23], s[8:9], v19, s24, v[20:21]
	v_or_b32_e32 v21, 1, v27
	v_mad_u64_u32 v[20:21], s[8:9], v21, s24, v[20:21]
	s_add_i32 s8, 0, 0x11000
	v_lshlrev_b32_e32 v19, 1, v19
	s_cmpk_gt_i32 s2, 0xff
	s_waitcnt vmcnt(15)
	ds_write_b128 v22, v[28:31]
	s_waitcnt vmcnt(13)
	ds_write_b128 v20, v[42:45]
	s_waitcnt vmcnt(11)
	ds_write_b128 v22, v[50:53] offset:17408
	s_waitcnt vmcnt(9)
	ds_write_b128 v20, v[58:61] offset:17408
	s_waitcnt vmcnt(7)
	ds_write_b128 v22, v[66:69] offset:34816
	s_waitcnt vmcnt(5)
	ds_write_b128 v20, v[74:77] offset:34816
	s_waitcnt vmcnt(3)
	ds_write_b128 v22, v[82:85] offset:52224
	s_waitcnt vmcnt(1)
; template <int HD, bool DIL>
; __device__ __forceinline__ void attn_compute(const bf16_t* Ks, const bf16_t* Vt, const bf16x8 (&qf)[HD / 32], int a, int quad, int fr,
;                                              const float* biasT, int kmin, f32x4 (&oacc)[HD / 16], float& mx_out, float& den_out) {
;     ...
;     for (int nt = 0; nt < 16; ++nt) {
;         s[nt] = (f32x4){0.f, 0.f, 0.f, 0.f};
; #pragma unroll
;         for (int ks = 0; ks < HD / 32; ++ks) {
;             const bf16x8 kf = *(const bf16x8*)(Ks + (16 * nt + fr) * (HD + 8) + quad * 8 + 32 * ks);
;             s[nt] = __builtin_amdgcn_mfma_f32_16x16x32_bf16(kf, qf[ks], s[nt], 0, 0, 0);
;         }
;     }
; __device__ __forceinline__ void cross_attn_unit(PP p, unsigned char* shm, int u, int l) {
;     ...
;         for (int i = 0; i < 8; ++i) { const int m = 2 * (tid >> 4) + (i & 1) + 64 * (i >> 1), ch = tid & 15;
;             const bf16_t* rowp = kvb + (size_t)(b * 256 + m) * 4096 + l * 1024 + xh * 128 + ch * 8; kq[i] = *(const u32x4*)rowp; vq[i] = *(const u32x4*)(rowp + 512); }
; #pragma unroll
;         for (int i = 0; i < 8; ++i) { const int m = 2 * (tid >> 4) + (i & 1) + 64 * (i >> 1), ch = tid & 15; *(u32x4*)(Ks + m * 136 + ch * 8) = kq[i]; }
; #pragma unroll
;         for (int i = 0; i < 8; i += 2) { const int m = 2 * (tid >> 4) + 64 * (i >> 1), ch = tid & 15; vt_store_pair(Vt, ch * 8, m, vq[i], vq[i + 1]); }
;     }
;     __syncthreads();
	ds_write_b128 v20, v[90:93] offset:52224
	v_mul_u32_u24_e32 v20, 0x218, v26
	v_add3_u32 v19, s8, v20, v19
	v_and_b32_e32 v20, 0xffff, v38
	v_and_b32_e32 v30, 0xffff, v54
	v_lshl_or_b32 v20, v46, 16, v20
	v_lshl_or_b32 v30, v62, 16, v30
	v_lshrrev_b32_e32 v21, 16, v38
	ds_write2_b32 v19, v20, v30 offset1:32
	v_lshrrev_b32_e32 v20, 16, v54
	v_and_or_b32 v21, v46, s10, v21
	v_and_or_b32 v20, v62, s10, v20
	v_and_b32_e32 v22, 0xffff, v39
	ds_write2_b32 v19, v21, v20 offset0:134 offset1:166
	v_and_b32_e32 v20, 0xffff, v55
	v_lshl_or_b32 v22, v47, 16, v22
	v_lshl_or_b32 v20, v63, 16, v20
	v_add_u32_e32 v21, 0x400, v19
	v_lshrrev_b32_e32 v23, 16, v39
	ds_write2_b32 v21, v22, v20 offset0:12 offset1:44
	v_lshrrev_b32_e32 v20, 16, v55
	v_and_or_b32 v23, v47, s10, v23
	v_and_or_b32 v20, v63, s10, v20
	v_and_b32_e32 v26, 0xffff, v40
	ds_write2_b32 v21, v23, v20 offset0:146 offset1:178
	v_and_b32_e32 v20, 0xffff, v56
	v_lshl_or_b32 v26, v48, 16, v26
	v_lshl_or_b32 v20, v64, 16, v20
	v_add_u32_e32 v22, 0x800, v19
	v_lshrrev_b32_e32 v27, 16, v40
	ds_write2_b32 v22, v26, v20 offset0:24 offset1:56
	v_lshrrev_b32_e32 v20, 16, v56
	v_and_or_b32 v27, v48, s10, v27
	v_and_or_b32 v20, v64, s10, v20
	v_and_b32_e32 v28, 0xffff, v41
	ds_write2_b32 v22, v27, v20 offset0:158 offset1:190
	v_and_b32_e32 v20, 0xffff, v57
	v_lshl_or_b32 v28, v49, 16, v28
	v_lshl_or_b32 v20, v65, 16, v20
	v_add_u32_e32 v23, 0xc00, v19
	v_lshrrev_b32_e32 v29, 16, v41
	ds_write2_b32 v23, v28, v20 offset0:36 offset1:68
	v_lshrrev_b32_e32 v20, 16, v57
	v_and_or_b32 v29, v49, s10, v29
	v_and_or_b32 v20, v65, s10, v20
	ds_write2_b32 v23, v29, v20 offset0:170 offset1:202
	v_and_b32_e32 v20, 0xffff, v70
	v_and_b32_e32 v33, 0xffff, v86
	v_lshl_or_b32 v20, v78, 16, v20
	s_waitcnt vmcnt(0)
	v_lshl_or_b32 v33, v94, 16, v33
	v_lshrrev_b32_e32 v26, 16, v70
	ds_write2_b32 v19, v20, v33 offset0:64 offset1:96
	v_lshrrev_b32_e32 v20, 16, v86
	v_and_or_b32 v26, v78, s10, v26
	v_and_or_b32 v20, v94, s10, v20
	v_and_b32_e32 v27, 0xffff, v71
	ds_write2_b32 v19, v26, v20 offset0:198 offset1:230
	v_and_b32_e32 v20, 0xffff, v87
	v_lshl_or_b32 v27, v79, 16, v27
	v_lshl_or_b32 v20, v95, 16, v20
	v_lshrrev_b32_e32 v28, 16, v71
	ds_write2_b32 v21, v27, v20 offset0:76 offset1:108
	v_lshrrev_b32_e32 v20, 16, v87
	v_and_or_b32 v28, v79, s10, v28
	v_and_or_b32 v20, v95, s10, v20
	v_and_b32_e32 v29, 0xffff, v72
	ds_write2_b32 v21, v28, v20 offset0:210 offset1:242
	v_and_b32_e32 v20, 0xffff, v88
	v_lshl_or_b32 v29, v80, 16, v29
	v_lshl_or_b32 v20, v96, 16, v20
	v_lshrrev_b32_e32 v30, 16, v72
	ds_write2_b32 v22, v29, v20 offset0:88 offset1:120
	v_lshrrev_b32_e32 v20, 16, v88
	v_and_or_b32 v30, v80, s10, v30
	v_and_or_b32 v20, v96, s10, v20
	v_and_b32_e32 v31, 0xffff, v73
	ds_write2_b32 v22, v30, v20 offset0:222 offset1:254
	v_and_b32_e32 v20, 0xffff, v89
	v_lshl_or_b32 v31, v81, 16, v31
	v_lshl_or_b32 v20, v97, 16, v20
	v_lshrrev_b32_e32 v32, 16, v73
	ds_write2_b32 v23, v31, v20 offset0:100 offset1:132
	v_lshrrev_b32_e32 v20, 16, v89
	v_and_or_b32 v32, v81, s10, v32
	v_and_or_b32 v20, v97, s10, v20
	v_add_u32_e32 v19, 0xe00, v19
	ds_write2_b32 v19, v32, v20 offset0:106 offset1:138
	v_mul_u32_u24_e32 v19, 0x110, v24
	v_add3_u32 v22, 0, v18, v19
	s_waitcnt lgkmcnt(0)
	s_barrier
	ds_read_b128 v[18:21], v22
	ds_read_b128 v[26:29], v22 offset:64
	s_waitcnt lgkmcnt(1)
	v_mfma_f32_16x16x32_bf16 v[18:21], v[18:21], v[2:5], 0
	ds_read_b128 v[30:33], v22 offset:4416
	ds_read_b128 v[38:41], v22 offset:8768
	ds_read_b128 v[42:45], v22 offset:13120
	s_waitcnt lgkmcnt(3)
	v_mfma_f32_16x16x32_bf16 v[18:21], v[26:29], v[6:9], v[18:21]
	ds_read_b128 v[26:29], v22 offset:128
	ds_read_b128 v[46:49], v22 offset:17472
	ds_read_b128 v[50:53], v22 offset:21824
	s_waitcnt lgkmcnt(2)
	v_mfma_f32_16x16x32_bf16 v[18:21], v[26:29], v[10:13], v[18:21]
	ds_read_b128 v[26:29], v22 offset:192
	ds_read_b128 v[54:57], v22 offset:26176
	ds_read_b128 v[58:61], v22 offset:30528
	s_waitcnt lgkmcnt(2)
	v_mfma_f32_16x16x32_bf16 v[18:21], v[26:29], v[14:17], v[18:21]
	ds_read_b128 v[26:29], v22 offset:4352
	ds_read_b128 v[62:65], v22 offset:34880
	ds_read_b128 v[66:69], v22 offset:39232
	s_waitcnt lgkmcnt(2)
	v_mfma_f32_16x16x32_bf16 v[26:29], v[26:29], v[2:5], 0
	ds_read_b128 v[70:73], v22 offset:43584
	ds_read_b128 v[74:77], v22 offset:47936
	ds_read_b128 v[78:81], v22 offset:52288
	v_mfma_f32_16x16x32_bf16 v[26:29], v[30:33], v[6:9], v[26:29]
	ds_read_b128 v[30:33], v22 offset:4480
	ds_read_b128 v[82:85], v22 offset:56640
	ds_read_b128 v[86:89], v22 offset:60992
	s_waitcnt lgkmcnt(2)
	v_mfma_f32_16x16x32_bf16 v[26:29], v[30:33], v[10:13], v[26:29]
	ds_read_b128 v[30:33], v22 offset:4544
	s_waitcnt lgkmcnt(0)
	v_mfma_f32_16x16x32_bf16 v[26:29], v[30:33], v[14:17], v[26:29]
	ds_read_b128 v[30:33], v22 offset:8704
	s_waitcnt lgkmcnt(0)
	v_mfma_f32_16x16x32_bf16 v[30:33], v[30:33], v[2:5], 0
	v_mfma_f32_16x16x32_bf16 v[30:33], v[38:41], v[6:9], v[30:33]
	ds_read_b128 v[38:41], v22 offset:8832
	s_waitcnt lgkmcnt(0)
	v_mfma_f32_16x16x32_bf16 v[30:33], v[38:41], v[10:13], v[30:33]
	ds_read_b128 v[38:41], v22 offset:8896
	s_waitcnt lgkmcnt(0)
	v_mfma_f32_16x16x32_bf16 v[30:33], v[38:41], v[14:17], v[30:33]
	ds_read_b128 v[38:41], v22 offset:13056
	s_waitcnt lgkmcnt(0)
	v_mfma_f32_16x16x32_bf16 v[38:41], v[38:41], v[2:5], 0
	v_mfma_f32_16x16x32_bf16 v[38:41], v[42:45], v[6:9], v[38:41]
	ds_read_b128 v[42:45], v22 offset:13184
	s_waitcnt lgkmcnt(0)
	v_mfma_f32_16x16x32_bf16 v[38:41], v[42:45], v[10:13], v[38:41]
	ds_read_b128 v[42:45], v22 offset:13248
	s_waitcnt lgkmcnt(0)
	v_mfma_f32_16x16x32_bf16 v[38:41], v[42:45], v[14:17], v[38:41]
	ds_read_b128 v[42:45], v22 offset:17408
	s_waitcnt lgkmcnt(0)
; template <int HD, bool DIL>
; __device__ __forceinline__ void attn_compute(const bf16_t* Ks, const bf16_t* Vt, const bf16x8 (&qf)[HD / 32], int a, int quad, int fr,
;                                              const float* biasT, int kmin, f32x4 (&oacc)[HD / 16], float& mx_out, float& den_out) {
;     ...
;     for (int nt = 0; nt < 16; ++nt) {
;         s[nt] = (f32x4){0.f, 0.f, 0.f, 0.f};
; #pragma unroll
;         for (int ks = 0; ks < HD / 32; ++ks) {
;             const bf16x8 kf = *(const bf16x8*)(Ks + (16 * nt + fr) * (HD + 8) + quad * 8 + 32 * ks);
;             s[nt] = __builtin_amdgcn_mfma_f32_16x16x32_bf16(kf, qf[ks], s[nt], 0, 0, 0);
;         }
;     }
	v_mfma_f32_16x16x32_bf16 v[42:45], v[42:45], v[2:5], 0
	v_mfma_f32_16x16x32_bf16 v[42:45], v[46:49], v[6:9], v[42:45]
	ds_read_b128 v[46:49], v22 offset:17536
	s_waitcnt lgkmcnt(0)
	v_mfma_f32_16x16x32_bf16 v[42:45], v[46:49], v[10:13], v[42:45]
	ds_read_b128 v[46:49], v22 offset:17600
	s_waitcnt lgkmcnt(0)
	v_mfma_f32_16x16x32_bf16 v[42:45], v[46:49], v[14:17], v[42:45]
	ds_read_b128 v[46:49], v22 offset:21760
	s_waitcnt lgkmcnt(0)
	v_mfma_f32_16x16x32_bf16 v[46:49], v[46:49], v[2:5], 0
	v_mfma_f32_16x16x32_bf16 v[46:49], v[50:53], v[6:9], v[46:49]
	ds_read_b128 v[50:53], v22 offset:21888
	s_waitcnt lgkmcnt(0)
	v_mfma_f32_16x16x32_bf16 v[46:49], v[50:53], v[10:13], v[46:49]
	ds_read_b128 v[50:53], v22 offset:21952
	s_waitcnt lgkmcnt(0)
	v_mfma_f32_16x16x32_bf16 v[46:49], v[50:53], v[14:17], v[46:49]
	ds_read_b128 v[50:53], v22 offset:26112
	s_waitcnt lgkmcnt(0)
	v_mfma_f32_16x16x32_bf16 v[50:53], v[50:53], v[2:5], 0
	v_mfma_f32_16x16x32_bf16 v[50:53], v[54:57], v[6:9], v[50:53]
	ds_read_b128 v[54:57], v22 offset:26240
	s_waitcnt lgkmcnt(0)
	v_mfma_f32_16x16x32_bf16 v[50:53], v[54:57], v[10:13], v[50:53]
	ds_read_b128 v[54:57], v22 offset:26304
	s_waitcnt lgkmcnt(0)
	v_mfma_f32_16x16x32_bf16 v[50:53], v[54:57], v[14:17], v[50:53]
	ds_read_b128 v[54:57], v22 offset:30464
	s_waitcnt lgkmcnt(0)
	v_mfma_f32_16x16x32_bf16 v[54:57], v[54:57], v[2:5], 0
	v_mfma_f32_16x16x32_bf16 v[54:57], v[58:61], v[6:9], v[54:57]
	ds_read_b128 v[58:61], v22 offset:30592
	s_waitcnt lgkmcnt(0)
	v_mfma_f32_16x16x32_bf16 v[54:57], v[58:61], v[10:13], v[54:57]
	ds_read_b128 v[58:61], v22 offset:30656
	s_waitcnt lgkmcnt(0)
	v_mfma_f32_16x16x32_bf16 v[54:57], v[58:61], v[14:17], v[54:57]
	ds_read_b128 v[58:61], v22 offset:34816
	s_waitcnt lgkmcnt(0)
	v_mfma_f32_16x16x32_bf16 v[58:61], v[58:61], v[2:5], 0
	v_mfma_f32_16x16x32_bf16 v[58:61], v[62:65], v[6:9], v[58:61]
	ds_read_b128 v[62:65], v22 offset:34944
	s_waitcnt lgkmcnt(0)
	v_mfma_f32_16x16x32_bf16 v[58:61], v[62:65], v[10:13], v[58:61]
	ds_read_b128 v[62:65], v22 offset:35008
	s_waitcnt lgkmcnt(0)
	v_mfma_f32_16x16x32_bf16 v[58:61], v[62:65], v[14:17], v[58:61]
	ds_read_b128 v[62:65], v22 offset:39168
	s_waitcnt lgkmcnt(0)
	v_mfma_f32_16x16x32_bf16 v[62:65], v[62:65], v[2:5], 0
	v_mfma_f32_16x16x32_bf16 v[62:65], v[66:69], v[6:9], v[62:65]
	ds_read_b128 v[66:69], v22 offset:39296
	s_waitcnt lgkmcnt(0)
	v_mfma_f32_16x16x32_bf16 v[62:65], v[66:69], v[10:13], v[62:65]
	ds_read_b128 v[66:69], v22 offset:39360
	s_waitcnt lgkmcnt(0)
	v_mfma_f32_16x16x32_bf16 v[62:65], v[66:69], v[14:17], v[62:65]
	ds_read_b128 v[66:69], v22 offset:43520
	s_waitcnt lgkmcnt(0)
	v_mfma_f32_16x16x32_bf16 v[66:69], v[66:69], v[2:5], 0
	v_mfma_f32_16x16x32_bf16 v[66:69], v[70:73], v[6:9], v[66:69]
	ds_read_b128 v[70:73], v22 offset:43648
	s_waitcnt lgkmcnt(0)
	v_mfma_f32_16x16x32_bf16 v[66:69], v[70:73], v[10:13], v[66:69]
	ds_read_b128 v[70:73], v22 offset:43712
	s_waitcnt lgkmcnt(0)
	v_mfma_f32_16x16x32_bf16 v[66:69], v[70:73], v[14:17], v[66:69]
	ds_read_b128 v[70:73], v22 offset:47872
	s_waitcnt lgkmcnt(0)
	v_mfma_f32_16x16x32_bf16 v[70:73], v[70:73], v[2:5], 0
	v_mfma_f32_16x16x32_bf16 v[70:73], v[74:77], v[6:9], v[70:73]
	ds_read_b128 v[74:77], v22 offset:48000
	s_waitcnt lgkmcnt(0)
	v_mfma_f32_16x16x32_bf16 v[70:73], v[74:77], v[10:13], v[70:73]
	ds_read_b128 v[74:77], v22 offset:48064
	s_waitcnt lgkmcnt(0)
	v_mfma_f32_16x16x32_bf16 v[70:73], v[74:77], v[14:17], v[70:73]
	ds_read_b128 v[74:77], v22 offset:52224
	s_waitcnt lgkmcnt(0)
	v_mfma_f32_16x16x32_bf16 v[74:77], v[74:77], v[2:5], 0
	v_mfma_f32_16x16x32_bf16 v[74:77], v[78:81], v[6:9], v[74:77]
	ds_read_b128 v[78:81], v22 offset:52352
	s_waitcnt lgkmcnt(0)
	v_mfma_f32_16x16x32_bf16 v[74:77], v[78:81], v[10:13], v[74:77]
	ds_read_b128 v[78:81], v22 offset:52416
	s_waitcnt lgkmcnt(0)
	v_mfma_f32_16x16x32_bf16 v[74:77], v[78:81], v[14:17], v[74:77]
	ds_read_b128 v[78:81], v22 offset:56576
	s_waitcnt lgkmcnt(0)
	v_mfma_f32_16x16x32_bf16 v[78:81], v[78:81], v[2:5], 0
	v_mfma_f32_16x16x32_bf16 v[78:81], v[82:85], v[6:9], v[78:81]
	ds_read_b128 v[82:85], v22 offset:56704
	s_waitcnt lgkmcnt(0)
	v_mfma_f32_16x16x32_bf16 v[78:81], v[82:85], v[10:13], v[78:81]
	ds_read_b128 v[82:85], v22 offset:56768
	s_waitcnt lgkmcnt(0)
	v_mfma_f32_16x16x32_bf16 v[78:81], v[82:85], v[14:17], v[78:81]
	ds_read_b128 v[82:85], v22 offset:60928
	s_waitcnt lgkmcnt(0)
	v_mfma_f32_16x16x32_bf16 v[82:85], v[82:85], v[2:5], 0
	v_mfma_f32_16x16x32_bf16 v[82:85], v[86:89], v[6:9], v[82:85]
	ds_read_b128 v[86:89], v22 offset:61056
	s_waitcnt lgkmcnt(0)
	v_mfma_f32_16x16x32_bf16 v[82:85], v[86:89], v[10:13], v[82:85]
	ds_read_b128 v[86:89], v22 offset:61120
	s_waitcnt lgkmcnt(0)
	v_mfma_f32_16x16x32_bf16 v[82:85], v[86:89], v[14:17], v[82:85]
	ds_read_b128 v[86:89], v22 offset:65280
	s_waitcnt lgkmcnt(0)
	v_mfma_f32_16x16x32_bf16 v[2:5], v[86:89], v[2:5], 0
	ds_read_b128 v[86:89], v22 offset:65344
	s_waitcnt lgkmcnt(0)
	v_mfma_f32_16x16x32_bf16 v[2:5], v[86:89], v[6:9], v[2:5]
	ds_read_b128 v[6:9], v22 offset:65408
	s_waitcnt lgkmcnt(0)
	v_mfma_f32_16x16x32_bf16 v[2:5], v[6:9], v[10:13], v[2:5]
	ds_read_b128 v[6:9], v22 offset:65472
	s_waitcnt lgkmcnt(0)
; template <int HD, bool DIL>
; __device__ __forceinline__ void attn_compute(const bf16_t* Ks, const bf16_t* Vt, const bf16x8 (&qf)[HD / 32], int a, int quad, int fr,
;                                              const float* biasT, int kmin, f32x4 (&oacc)[HD / 16], float& mx_out, float& den_out) {
;     ...
;     float mx = -3.0e38f;
;     const float* tb = DIL ? (biasT + (127 - a + 4 * quad)) : nullptr;
; #pragma unroll
;     for (int nt = 0; nt < 16; ++nt)
; #pragma unroll
;         for (int j = 0; j < 4; ++j) {
;             float v = s[nt][j];
;             if (DIL) {
;                 v = v * 0.18033688011112042f + tb[16 * nt + j];
;                 if (nt < 8) v = kmin ? -1.0e30f : v;
;             }
;             s[nt][j] = v; mx = fmaxf(mx, v);
;         }
;     mx = fmaxf(mx, __shfl_xor(mx, 16)); mx = fmaxf(mx, __shfl_xor(mx, 32));
;     float sum = 0.f;
; #pragma unroll
;     for (int nt = 0; nt < 16; ++nt)
; #pragma unroll
;         for (int j = 0; j < 4; ++j) { const float pv = __builtin_amdgcn_exp2f(s[nt][j] - mx); s[nt][j] = pv; sum += pv; }
;     sum += __shfl_xor(sum, 16); sum += __shfl_xor(sum, 32);
	v_mfma_f32_16x16x32_bf16 v[2:5], v[6:9], v[14:17], v[2:5]
	v_max3_f32 v6, v18, s22, v19
	v_max3_f32 v6, v6, v20, v21
	v_max3_f32 v6, v6, v26, v27
	v_max3_f32 v6, v6, v28, v29
	v_max3_f32 v6, v6, v30, v31
	v_max3_f32 v6, v6, v32, v33
	v_max3_f32 v6, v6, v38, v39
	v_max3_f32 v6, v6, v40, v41
	v_max3_f32 v6, v6, v42, v43
	v_max3_f32 v6, v6, v44, v45
	v_max3_f32 v6, v6, v46, v47
	v_max3_f32 v6, v6, v48, v49
	v_max3_f32 v6, v6, v50, v51
	v_max3_f32 v6, v6, v52, v53
	v_max3_f32 v6, v6, v54, v55
	v_max3_f32 v6, v6, v56, v57
	v_max3_f32 v6, v6, v58, v59
	v_max3_f32 v6, v6, v60, v61
	v_max3_f32 v6, v6, v62, v63
	v_max3_f32 v6, v6, v64, v65
	v_max3_f32 v6, v6, v66, v67
	v_max3_f32 v6, v6, v68, v69
	v_max3_f32 v6, v6, v70, v71
	v_max3_f32 v6, v6, v72, v73
	v_max3_f32 v6, v6, v74, v75
	v_max3_f32 v6, v6, v76, v77
	v_max3_f32 v6, v6, v78, v79
	v_max3_f32 v6, v6, v80, v81
	v_max3_f32 v6, v6, v82, v83
	v_max3_f32 v6, v6, v84, v85
	v_max3_f32 v6, v6, v2, v3
	v_max3_f32 v6, v6, v4, v5
	ds_bpermute_b32 v7, v25, v6
	s_waitcnt lgkmcnt(0)
	v_max_f32_e32 v7, v7, v7
	v_max_f32_e32 v6, v6, v7
	ds_bpermute_b32 v7, v34, v6
	s_waitcnt lgkmcnt(0)
	v_max_f32_e32 v7, v7, v7
	v_max_f32_e32 v6, v6, v7
	v_sub_f32_e32 v7, v18, v6
	v_exp_f32_e32 v7, v7
	v_sub_f32_e32 v9, v19, v6
	v_exp_f32_e32 v9, v9
	v_sub_f32_e32 v10, v20, v6
	v_exp_f32_e32 v10, v10
	v_sub_f32_e32 v11, v21, v6
	v_exp_f32_e32 v11, v11
	v_sub_f32_e32 v12, v26, v6
	v_add_f32_e32 v8, 0, v7
	v_exp_f32_e32 v12, v12
	v_sub_f32_e32 v13, v27, v6
	v_add_f32_e32 v8, v9, v8
	v_exp_f32_e32 v13, v13
	v_sub_f32_e32 v14, v28, v6
	v_add_f32_e32 v8, v10, v8
	v_exp_f32_e32 v14, v14
	v_sub_f32_e32 v15, v29, v6
	v_add_f32_e32 v8, v11, v8
	v_exp_f32_e32 v15, v15
	v_sub_f32_e32 v16, v30, v6
	v_add_f32_e32 v8, v12, v8
	v_exp_f32_e32 v35, v16
	v_sub_f32_e32 v16, v31, v6
	v_add_f32_e32 v8, v13, v8
	v_exp_f32_e32 v86, v16
	v_sub_f32_e32 v16, v32, v6
	v_add_f32_e32 v8, v14, v8
	v_exp_f32_e32 v87, v16
	v_sub_f32_e32 v16, v33, v6
	v_add_f32_e32 v8, v15, v8
	v_exp_f32_e32 v88, v16
	v_sub_f32_e32 v16, v38, v6
	v_add_f32_e32 v8, v35, v8
	v_exp_f32_e32 v89, v16
	v_sub_f32_e32 v16, v39, v6
	v_add_f32_e32 v8, v86, v8
	v_exp_f32_e32 v90, v16
	v_sub_f32_e32 v16, v40, v6
	v_add_f32_e32 v8, v87, v8
	v_exp_f32_e32 v91, v16
	v_sub_f32_e32 v16, v41, v6
	v_add_f32_e32 v8, v88, v8
	v_exp_f32_e32 v92, v16
	v_sub_f32_e32 v16, v42, v6
	v_add_f32_e32 v8, v89, v8
	v_exp_f32_e32 v93, v16
	v_sub_f32_e32 v16, v43, v6
	v_add_f32_e32 v8, v90, v8
	v_exp_f32_e32 v94, v16
	v_sub_f32_e32 v16, v44, v6
	v_add_f32_e32 v8, v91, v8
	v_exp_f32_e32 v95, v16
	v_sub_f32_e32 v16, v45, v6
	v_add_f32_e32 v8, v92, v8
	v_exp_f32_e32 v96, v16
	v_sub_f32_e32 v16, v46, v6
	v_add_f32_e32 v8, v93, v8
	v_exp_f32_e32 v46, v16
	v_sub_f32_e32 v16, v47, v6
	v_add_f32_e32 v8, v94, v8
	v_exp_f32_e32 v47, v16
	v_sub_f32_e32 v16, v48, v6
	v_add_f32_e32 v8, v95, v8
	v_exp_f32_e32 v48, v16
	v_sub_f32_e32 v16, v49, v6
	v_add_f32_e32 v8, v96, v8
	v_exp_f32_e32 v49, v16
	v_sub_f32_e32 v16, v50, v6
	v_add_f32_e32 v8, v46, v8
	v_exp_f32_e32 v50, v16
	v_sub_f32_e32 v16, v51, v6
	v_add_f32_e32 v8, v47, v8
	v_exp_f32_e32 v51, v16
	v_sub_f32_e32 v16, v52, v6
	v_add_f32_e32 v8, v48, v8
	v_exp_f32_e32 v52, v16
	v_sub_f32_e32 v16, v53, v6
	v_add_f32_e32 v8, v49, v8
	v_exp_f32_e32 v53, v16
	v_sub_f32_e32 v16, v54, v6
	v_add_f32_e32 v8, v50, v8
	v_exp_f32_e32 v54, v16
	v_sub_f32_e32 v16, v55, v6
	v_add_f32_e32 v8, v51, v8
	v_exp_f32_e32 v55, v16
	v_sub_f32_e32 v16, v56, v6
	v_add_f32_e32 v8, v52, v8
	v_exp_f32_e32 v56, v16
	v_sub_f32_e32 v16, v57, v6
	v_add_f32_e32 v8, v53, v8
	v_exp_f32_e32 v57, v16
	v_sub_f32_e32 v16, v58, v6
	v_add_f32_e32 v8, v54, v8
	v_exp_f32_e32 v58, v16
	v_sub_f32_e32 v16, v59, v6
	v_add_f32_e32 v8, v55, v8
	v_exp_f32_e32 v59, v16
	v_sub_f32_e32 v16, v60, v6
	v_add_f32_e32 v8, v56, v8
	v_exp_f32_e32 v60, v16
	v_sub_f32_e32 v16, v61, v6
	v_add_f32_e32 v8, v57, v8
	v_exp_f32_e32 v61, v16
	v_sub_f32_e32 v16, v62, v6
	v_add_f32_e32 v8, v58, v8
	v_exp_f32_e32 v62, v16
	v_sub_f32_e32 v16, v63, v6
	v_add_f32_e32 v8, v59, v8
	v_exp_f32_e32 v63, v16
	v_sub_f32_e32 v16, v64, v6
	v_add_f32_e32 v8, v60, v8
	v_exp_f32_e32 v64, v16
	v_sub_f32_e32 v16, v65, v6
	v_add_f32_e32 v8, v61, v8
	v_exp_f32_e32 v65, v16
	v_sub_f32_e32 v16, v66, v6
	v_add_f32_e32 v8, v62, v8
	v_exp_f32_e32 v66, v16
	v_sub_f32_e32 v16, v67, v6
	v_add_f32_e32 v8, v63, v8
	v_exp_f32_e32 v67, v16
	v_sub_f32_e32 v16, v68, v6
	v_add_f32_e32 v8, v64, v8
	v_exp_f32_e32 v68, v16
	v_sub_f32_e32 v16, v69, v6
	v_add_f32_e32 v8, v65, v8
	v_exp_f32_e32 v69, v16
	v_sub_f32_e32 v16, v70, v6
	v_add_f32_e32 v8, v66, v8
	v_exp_f32_e32 v70, v16
	v_sub_f32_e32 v16, v71, v6
	v_add_f32_e32 v8, v67, v8
	v_exp_f32_e32 v71, v16
	v_sub_f32_e32 v16, v72, v6
	v_add_f32_e32 v8, v68, v8
	v_exp_f32_e32 v72, v16
	v_sub_f32_e32 v16, v73, v6
	v_add_f32_e32 v8, v69, v8
	v_exp_f32_e32 v73, v16
	v_sub_f32_e32 v16, v74, v6
	v_add_f32_e32 v8, v70, v8
	v_exp_f32_e32 v74, v16
	v_sub_f32_e32 v16, v75, v6
	v_add_f32_e32 v8, v71, v8
	v_exp_f32_e32 v75, v16
	v_sub_f32_e32 v16, v76, v6
	v_add_f32_e32 v8, v72, v8
	v_exp_f32_e32 v76, v16
	v_sub_f32_e32 v16, v77, v6
	v_add_f32_e32 v8, v73, v8
	v_exp_f32_e32 v77, v16
	v_sub_f32_e32 v16, v78, v6
	v_add_f32_e32 v8, v74, v8
	v_exp_f32_e32 v78, v16
	v_sub_f32_e32 v16, v79, v6
	v_add_f32_e32 v8, v75, v8
	v_exp_f32_e32 v79, v16
	v_sub_f32_e32 v16, v80, v6
	v_add_f32_e32 v8, v76, v8
	v_exp_f32_e32 v80, v16
	v_sub_f32_e32 v16, v81, v6
	v_add_f32_e32 v8, v77, v8
	v_exp_f32_e32 v81, v16
	v_sub_f32_e32 v16, v82, v6
	v_add_f32_e32 v8, v78, v8
	v_exp_f32_e32 v82, v16
	v_sub_f32_e32 v16, v83, v6
	v_add_f32_e32 v8, v79, v8
	v_exp_f32_e32 v83, v16
	v_sub_f32_e32 v16, v84, v6
	v_add_f32_e32 v8, v80, v8
	v_exp_f32_e32 v84, v16
	v_sub_f32_e32 v16, v85, v6
	v_add_f32_e32 v8, v81, v8
	v_exp_f32_e32 v85, v16
	v_sub_f32_e32 v2, v2, v6
	v_add_f32_e32 v8, v82, v8
	v_exp_f32_e32 v97, v2
	v_sub_f32_e32 v3, v3, v6
	v_add_f32_e32 v8, v83, v8
	v_exp_f32_e32 v98, v3
	v_sub_f32_e32 v3, v4, v6
	v_add_f32_e32 v8, v84, v8
	v_exp_f32_e32 v99, v3
	v_sub_f32_e32 v3, v5, v6
	v_add_f32_e32 v8, v85, v8
	v_exp_f32_e32 v100, v3
	v_add_f32_e32 v2, v97, v8
	v_add_f32_e32 v2, v98, v2
	v_add_f32_e32 v2, v99, v2
	v_add_f32_e32 v2, v100, v2
	ds_bpermute_b32 v3, v25, v2
	v_mul_u32_u24_e32 v6, 0x218, v24
	v_add3_u32 v102, s8, v0, v6
	v_add_u32_e32 v103, 0x2000, v102
	v_add_u32_e32 v104, 0x4000, v102
	s_waitcnt lgkmcnt(0)
; __device__ __forceinline__ unsigned pk2(float lo, float hi) { const hf32x2 v = {lo, hi}; return __builtin_bit_cast(unsigned, __builtin_convertvector(v, hbf16x2)); }
; template <int HD, bool DIL>
; __device__ __forceinline__ void attn_compute(const bf16_t* Ks, const bf16_t* Vt, const bf16x8 (&qf)[HD / 32], int a, int quad, int fr,
;                                              const float* biasT, int kmin, f32x4 (&oacc)[HD / 16], float& mx_out, float& den_out) {
;     ...
;     float sum = 0.f;
; #pragma unroll
;     for (int nt = 0; nt < 16; ++nt)
; #pragma unroll
;         for (int j = 0; j < 4; ++j) { const float pv = __builtin_amdgcn_exp2f(s[nt][j] - mx); s[nt][j] = pv; sum += pv; }
;     sum += __shfl_xor(sum, 16); sum += __shfl_xor(sum, 32);
; #pragma unroll
;     for (int dt = 0; dt < HD / 16; ++dt) oacc[dt] = (f32x4){0.f, 0.f, 0.f, 0.f};
; #pragma unroll
;     for (int k2 = 0; k2 < 8; ++k2) {
;         u32x4 pp; pp.x = pk2(s[2 * k2][0], s[2 * k2][1]); pp.y = pk2(s[2 * k2][2], s[2 * k2][3]); pp.z = pk2(s[2 * k2 + 1][0], s[2 * k2 + 1][1]); pp.w = pk2(s[2 * k2 + 1][2], s[2 * k2 + 1][3]);
;         const bf16x8 pf = __builtin_bit_cast(bf16x8, pp);
; #pragma unroll
;         for (int dt = 0; dt < HD / 16; ++dt) {
;             const bf16_t* vp = Vt + (16 * dt + fr) * VS + 32 * k2 + quad * 4;
;             const u32x2 lo = *(const u32x2*)vp, hi = *(const u32x2*)(vp + 16);
;             u32x4 vv; vv.x = lo.x; vv.y = lo.y; vv.z = hi.x; vv.w = hi.y;
;             oacc[dt] = __builtin_amdgcn_mfma_f32_16x16x32_bf16(__builtin_bit_cast(bf16x8, vv), pf, oacc[dt], 0, 0, 0);
;         }
;     }
	v_add_f32_e32 v101, v2, v3
	v_cvt_pk_bf16_f32 v2, v7, v9
	ds_read2_b64 v[6:9], v102 offset1:4
	v_add_u32_e32 v105, 0x6000, v102
	v_add_u32_e32 v106, 0x8000, v102
	v_add_u32_e32 v107, 0xa000, v102
	v_add_u32_e32 v108, 0xc800, v102
	v_add_u32_e32 v109, 0xe800, v102
	v_cvt_pk_bf16_f32 v3, v10, v11
	v_cvt_pk_bf16_f32 v4, v12, v13
	v_cvt_pk_bf16_f32 v5, v14, v15
	ds_read2_b64 v[10:13], v103 offset0:48 offset1:52
	ds_read2_b64 v[14:17], v104 offset0:96 offset1:100
	ds_read2_b64 v[18:21], v105 offset0:144 offset1:148
	ds_read2_b64 v[22:25], v106 offset0:192 offset1:196
	ds_read2_b64 v[26:29], v107 offset0:240 offset1:244
	ds_read2_b64 v[30:33], v108 offset0:32 offset1:36
	ds_read2_b64 v[38:41], v109 offset0:80 offset1:84
	ds_read2_b64 v[42:45], v102 offset0:8 offset1:12
	s_waitcnt lgkmcnt(8)
	v_mfma_f32_16x16x32_bf16 v[6:9], v[6:9], v[2:5], 0
	ds_bpermute_b32 v34, v34, v101
	s_waitcnt lgkmcnt(0)
	v_add_f32_e32 v34, v101, v34
	v_mfma_f32_16x16x32_bf16 v[10:13], v[10:13], v[2:5], 0
	v_mfma_f32_16x16x32_bf16 v[14:17], v[14:17], v[2:5], 0
	v_mfma_f32_16x16x32_bf16 v[18:21], v[18:21], v[2:5], 0
	v_mfma_f32_16x16x32_bf16 v[22:25], v[22:25], v[2:5], 0
	v_mfma_f32_16x16x32_bf16 v[26:29], v[26:29], v[2:5], 0
	v_mfma_f32_16x16x32_bf16 v[30:33], v[30:33], v[2:5], 0
	v_mfma_f32_16x16x32_bf16 v[2:5], v[38:41], v[2:5], 0
	v_cvt_pk_bf16_f32 v38, v35, v86
	v_cvt_pk_bf16_f32 v39, v87, v88
	v_cvt_pk_bf16_f32 v40, v89, v90
	v_cvt_pk_bf16_f32 v41, v91, v92
	v_add_u32_e32 v35, 0xa800, v102
	s_nop 0
	v_mfma_f32_16x16x32_bf16 v[6:9], v[42:45], v[38:41], v[6:9]
	ds_read2_b64 v[42:45], v103 offset0:56 offset1:60
	s_waitcnt lgkmcnt(0)
	v_mfma_f32_16x16x32_bf16 v[10:13], v[42:45], v[38:41], v[10:13]
	ds_read2_b64 v[42:45], v104 offset0:104 offset1:108
	s_waitcnt lgkmcnt(0)
	v_mfma_f32_16x16x32_bf16 v[14:17], v[42:45], v[38:41], v[14:17]
	ds_read2_b64 v[42:45], v105 offset0:152 offset1:156
	s_waitcnt lgkmcnt(0)
	v_mfma_f32_16x16x32_bf16 v[18:21], v[42:45], v[38:41], v[18:21]
	ds_read2_b64 v[42:45], v106 offset0:200 offset1:204
	s_waitcnt lgkmcnt(0)
	v_mfma_f32_16x16x32_bf16 v[22:25], v[42:45], v[38:41], v[22:25]
	ds_read2_b64 v[42:45], v107 offset0:248 offset1:252
	s_waitcnt lgkmcnt(0)
	v_mfma_f32_16x16x32_bf16 v[26:29], v[42:45], v[38:41], v[26:29]
	ds_read2_b64 v[42:45], v108 offset0:40 offset1:44
	s_waitcnt lgkmcnt(0)
	v_mfma_f32_16x16x32_bf16 v[30:33], v[42:45], v[38:41], v[30:33]
	ds_read2_b64 v[42:45], v109 offset0:88 offset1:92
	s_waitcnt lgkmcnt(0)
	v_mfma_f32_16x16x32_bf16 v[2:5], v[42:45], v[38:41], v[2:5]
	ds_read2_b64 v[42:45], v102 offset0:16 offset1:20
	v_cvt_pk_bf16_f32 v38, v93, v94
	v_cvt_pk_bf16_f32 v39, v95, v96
	v_cvt_pk_bf16_f32 v40, v46, v47
	v_cvt_pk_bf16_f32 v41, v48, v49
	s_waitcnt lgkmcnt(0)
	s_nop 0
	v_mfma_f32_16x16x32_bf16 v[6:9], v[42:45], v[38:41], v[6:9]
	ds_read2_b64 v[42:45], v103 offset0:64 offset1:68
	s_waitcnt lgkmcnt(0)
	v_mfma_f32_16x16x32_bf16 v[10:13], v[42:45], v[38:41], v[10:13]
	ds_read2_b64 v[42:45], v104 offset0:112 offset1:116
	s_waitcnt lgkmcnt(0)
	v_mfma_f32_16x16x32_bf16 v[14:17], v[42:45], v[38:41], v[14:17]
	ds_read2_b64 v[42:45], v105 offset0:160 offset1:164
	s_waitcnt lgkmcnt(0)
	v_mfma_f32_16x16x32_bf16 v[18:21], v[42:45], v[38:41], v[18:21]
	ds_read2_b64 v[42:45], v106 offset0:208 offset1:212
	s_waitcnt lgkmcnt(0)
	v_mfma_f32_16x16x32_bf16 v[22:25], v[42:45], v[38:41], v[22:25]
	ds_read2_b64 v[42:45], v35 offset1:4
	s_waitcnt lgkmcnt(0)
	v_mfma_f32_16x16x32_bf16 v[26:29], v[42:45], v[38:41], v[26:29]
	ds_read2_b64 v[42:45], v108 offset0:48 offset1:52
	s_waitcnt lgkmcnt(0)
	v_mfma_f32_16x16x32_bf16 v[30:33], v[42:45], v[38:41], v[30:33]
	ds_read2_b64 v[42:45], v109 offset0:96 offset1:100
	s_waitcnt lgkmcnt(0)
	v_mfma_f32_16x16x32_bf16 v[2:5], v[42:45], v[38:41], v[2:5]
	ds_read2_b64 v[42:45], v102 offset0:24 offset1:28
	v_cvt_pk_bf16_f32 v38, v50, v51
	v_cvt_pk_bf16_f32 v39, v52, v53
	v_cvt_pk_bf16_f32 v40, v54, v55
	v_cvt_pk_bf16_f32 v41, v56, v57
	s_waitcnt lgkmcnt(0)
	s_nop 0
	v_mfma_f32_16x16x32_bf16 v[6:9], v[42:45], v[38:41], v[6:9]
	ds_read2_b64 v[42:45], v103 offset0:72 offset1:76
	s_waitcnt lgkmcnt(0)
	v_mfma_f32_16x16x32_bf16 v[10:13], v[42:45], v[38:41], v[10:13]
	ds_read2_b64 v[42:45], v104 offset0:120 offset1:124
	s_waitcnt lgkmcnt(0)
	v_mfma_f32_16x16x32_bf16 v[14:17], v[42:45], v[38:41], v[14:17]
	ds_read2_b64 v[42:45], v105 offset0:168 offset1:172
	s_waitcnt lgkmcnt(0)
	v_mfma_f32_16x16x32_bf16 v[18:21], v[42:45], v[38:41], v[18:21]
	ds_read2_b64 v[42:45], v106 offset0:216 offset1:220
	s_waitcnt lgkmcnt(0)
	v_mfma_f32_16x16x32_bf16 v[22:25], v[42:45], v[38:41], v[22:25]
	ds_read2_b64 v[42:45], v35 offset0:8 offset1:12
	s_waitcnt lgkmcnt(0)
	v_mfma_f32_16x16x32_bf16 v[26:29], v[42:45], v[38:41], v[26:29]
	ds_read2_b64 v[42:45], v108 offset0:56 offset1:60
	s_waitcnt lgkmcnt(0)
	v_mfma_f32_16x16x32_bf16 v[30:33], v[42:45], v[38:41], v[30:33]
	ds_read2_b64 v[42:45], v109 offset0:104 offset1:108
	s_waitcnt lgkmcnt(0)
	v_mfma_f32_16x16x32_bf16 v[2:5], v[42:45], v[38:41], v[2:5]
	ds_read2_b64 v[42:45], v102 offset0:32 offset1:36
	v_cvt_pk_bf16_f32 v38, v58, v59
	v_cvt_pk_bf16_f32 v39, v60, v61
	v_cvt_pk_bf16_f32 v40, v62, v63
	v_cvt_pk_bf16_f32 v41, v64, v65
	s_waitcnt lgkmcnt(0)
	s_nop 0
	v_mfma_f32_16x16x32_bf16 v[6:9], v[42:45], v[38:41], v[6:9]
	ds_read2_b64 v[42:45], v103 offset0:80 offset1:84
	s_waitcnt lgkmcnt(0)
	v_mfma_f32_16x16x32_bf16 v[10:13], v[42:45], v[38:41], v[10:13]
	ds_read2_b64 v[42:45], v104 offset0:128 offset1:132
	s_waitcnt lgkmcnt(0)
	v_mfma_f32_16x16x32_bf16 v[14:17], v[42:45], v[38:41], v[14:17]
	ds_read2_b64 v[42:45], v105 offset0:176 offset1:180
	s_waitcnt lgkmcnt(0)
; __device__ __forceinline__ unsigned pk2(float lo, float hi) { const hf32x2 v = {lo, hi}; return __builtin_bit_cast(unsigned, __builtin_convertvector(v, hbf16x2)); }
; template <int HD, bool DIL>
; __device__ __forceinline__ void attn_compute(const bf16_t* Ks, const bf16_t* Vt, const bf16x8 (&qf)[HD / 32], int a, int quad, int fr,
;                                              const float* biasT, int kmin, f32x4 (&oacc)[HD / 16], float& mx_out, float& den_out) {
;     ...
;     for (int k2 = 0; k2 < 8; ++k2) {
;         u32x4 pp; pp.x = pk2(s[2 * k2][0], s[2 * k2][1]); pp.y = pk2(s[2 * k2][2], s[2 * k2][3]); pp.z = pk2(s[2 * k2 + 1][0], s[2 * k2 + 1][1]); pp.w = pk2(s[2 * k2 + 1][2], s[2 * k2 + 1][3]);
;         const bf16x8 pf = __builtin_bit_cast(bf16x8, pp);
; #pragma unroll
;         for (int dt = 0; dt < HD / 16; ++dt) {
;             const bf16_t* vp = Vt + (16 * dt + fr) * VS + 32 * k2 + quad * 4;
;             const u32x2 lo = *(const u32x2*)vp, hi = *(const u32x2*)(vp + 16);
;             u32x4 vv; vv.x = lo.x; vv.y = lo.y; vv.z = hi.x; vv.w = hi.y;
;             oacc[dt] = __builtin_amdgcn_mfma_f32_16x16x32_bf16(__builtin_bit_cast(bf16x8, vv), pf, oacc[dt], 0, 0, 0);
;         }
;     }
; __device__ __forceinline__ void cross_attn_unit(PP p, unsigned char* shm, int u, int l) {
;     ...
;     const float inv = 1.0f / den;
;     bf16_t* ox = (bf16_t*)(p->ws + WS_OX) + rowq * 512 + xh * 128 + quad * 4;
; #pragma unroll
;     for (int dt = 0; dt < 8; ++dt) { u32x2 o; o.x = pk2(oacc[dt][0] * inv, oacc[dt][1] * inv); o.y = pk2(oacc[dt][2] * inv, oacc[dt][3] * inv); *(u32x2*)(ox + 16 * dt) = o; }
;     __syncthreads();
	v_mfma_f32_16x16x32_bf16 v[18:21], v[42:45], v[38:41], v[18:21]
	ds_read2_b64 v[42:45], v106 offset0:224 offset1:228
	s_waitcnt lgkmcnt(0)
	v_mfma_f32_16x16x32_bf16 v[22:25], v[42:45], v[38:41], v[22:25]
	ds_read2_b64 v[42:45], v35 offset0:16 offset1:20
	s_waitcnt lgkmcnt(0)
	v_mfma_f32_16x16x32_bf16 v[26:29], v[42:45], v[38:41], v[26:29]
	ds_read2_b64 v[42:45], v108 offset0:64 offset1:68
	s_waitcnt lgkmcnt(0)
	v_mfma_f32_16x16x32_bf16 v[30:33], v[42:45], v[38:41], v[30:33]
	ds_read2_b64 v[42:45], v109 offset0:112 offset1:116
	s_waitcnt lgkmcnt(0)
	v_mfma_f32_16x16x32_bf16 v[2:5], v[42:45], v[38:41], v[2:5]
	ds_read2_b64 v[42:45], v102 offset0:40 offset1:44
	v_cvt_pk_bf16_f32 v38, v66, v67
	v_cvt_pk_bf16_f32 v39, v68, v69
	v_cvt_pk_bf16_f32 v40, v70, v71
	v_cvt_pk_bf16_f32 v41, v72, v73
	s_waitcnt lgkmcnt(0)
	s_nop 0
	v_mfma_f32_16x16x32_bf16 v[6:9], v[42:45], v[38:41], v[6:9]
	ds_read2_b64 v[42:45], v103 offset0:88 offset1:92
	s_waitcnt lgkmcnt(0)
	v_mfma_f32_16x16x32_bf16 v[10:13], v[42:45], v[38:41], v[10:13]
	ds_read2_b64 v[42:45], v104 offset0:136 offset1:140
	s_waitcnt lgkmcnt(0)
	v_mfma_f32_16x16x32_bf16 v[14:17], v[42:45], v[38:41], v[14:17]
	ds_read2_b64 v[42:45], v105 offset0:184 offset1:188
	s_waitcnt lgkmcnt(0)
	v_mfma_f32_16x16x32_bf16 v[18:21], v[42:45], v[38:41], v[18:21]
	ds_read2_b64 v[42:45], v106 offset0:232 offset1:236
	s_waitcnt lgkmcnt(0)
	v_mfma_f32_16x16x32_bf16 v[22:25], v[42:45], v[38:41], v[22:25]
	ds_read2_b64 v[42:45], v35 offset0:24 offset1:28
	s_waitcnt lgkmcnt(0)
	v_mfma_f32_16x16x32_bf16 v[26:29], v[42:45], v[38:41], v[26:29]
	ds_read2_b64 v[42:45], v108 offset0:72 offset1:76
	s_waitcnt lgkmcnt(0)
	v_mfma_f32_16x16x32_bf16 v[30:33], v[42:45], v[38:41], v[30:33]
	ds_read2_b64 v[42:45], v109 offset0:120 offset1:124
	s_waitcnt lgkmcnt(0)
	v_mfma_f32_16x16x32_bf16 v[2:5], v[42:45], v[38:41], v[2:5]
	ds_read2_b64 v[42:45], v102 offset0:48 offset1:52
	v_cvt_pk_bf16_f32 v38, v74, v75
	v_cvt_pk_bf16_f32 v39, v76, v77
	v_cvt_pk_bf16_f32 v40, v78, v79
	v_cvt_pk_bf16_f32 v41, v80, v81
	s_waitcnt lgkmcnt(0)
	s_nop 0
	v_mfma_f32_16x16x32_bf16 v[6:9], v[42:45], v[38:41], v[6:9]
	ds_read2_b64 v[42:45], v103 offset0:96 offset1:100
	s_waitcnt lgkmcnt(0)
	v_mfma_f32_16x16x32_bf16 v[10:13], v[42:45], v[38:41], v[10:13]
	ds_read2_b64 v[42:45], v104 offset0:144 offset1:148
	s_waitcnt lgkmcnt(0)
	v_mfma_f32_16x16x32_bf16 v[14:17], v[42:45], v[38:41], v[14:17]
	ds_read2_b64 v[42:45], v105 offset0:192 offset1:196
	s_waitcnt lgkmcnt(0)
	v_mfma_f32_16x16x32_bf16 v[18:21], v[42:45], v[38:41], v[18:21]
	ds_read2_b64 v[42:45], v106 offset0:240 offset1:244
	s_waitcnt lgkmcnt(0)
	v_mfma_f32_16x16x32_bf16 v[42:45], v[42:45], v[38:41], v[22:25]
	s_nop 2
	ds_read2_b64 v[22:25], v35 offset0:32 offset1:36
	s_waitcnt lgkmcnt(0)
	v_mfma_f32_16x16x32_bf16 v[46:49], v[22:25], v[38:41], v[26:29]
	ds_read2_b64 v[22:25], v108 offset0:80 offset1:84
	s_waitcnt lgkmcnt(0)
	v_mfma_f32_16x16x32_bf16 v[50:53], v[22:25], v[38:41], v[30:33]
	ds_read2_b64 v[22:25], v109 offset0:128 offset1:132
	s_waitcnt lgkmcnt(0)
	v_mfma_f32_16x16x32_bf16 v[2:5], v[22:25], v[38:41], v[2:5]
	ds_read2_b64 v[22:25], v102 offset0:56 offset1:60
	v_cvt_pk_bf16_f32 v38, v82, v83
	v_cvt_pk_bf16_f32 v39, v84, v85
	v_cvt_pk_bf16_f32 v40, v97, v98
	v_cvt_pk_bf16_f32 v41, v99, v100
	s_waitcnt lgkmcnt(0)
	s_nop 0
	v_mfma_f32_16x16x32_bf16 v[30:33], v[22:25], v[38:41], v[6:9]
	s_nop 2
	ds_read2_b64 v[6:9], v103 offset0:104 offset1:108
	s_waitcnt lgkmcnt(0)
	v_mfma_f32_16x16x32_bf16 v[26:29], v[6:9], v[38:41], v[10:13]
	ds_read2_b64 v[6:9], v104 offset0:152 offset1:156
	s_waitcnt lgkmcnt(0)
	v_mfma_f32_16x16x32_bf16 v[22:25], v[6:9], v[38:41], v[14:17]
	ds_read2_b64 v[6:9], v105 offset0:200 offset1:204
	s_waitcnt lgkmcnt(0)
	v_mfma_f32_16x16x32_bf16 v[18:21], v[6:9], v[38:41], v[18:21]
	ds_read2_b64 v[6:9], v106 offset0:248 offset1:252
	s_waitcnt lgkmcnt(0)
	v_mfma_f32_16x16x32_bf16 v[14:17], v[6:9], v[38:41], v[42:45]
	ds_read2_b64 v[6:9], v35 offset0:40 offset1:44
	s_nop 1
	ds_read2_b64 v[42:45], v109 offset0:136 offset1:140
	v_div_scale_f32 v35, s[8:9], v34, v34, 1.0
	s_waitcnt lgkmcnt(1)
	v_mfma_f32_16x16x32_bf16 v[10:13], v[6:9], v[38:41], v[46:49]
	ds_read2_b64 v[6:9], v108 offset0:88 offset1:92
	s_mov_b64 s[8:9], 0x286c0000
	s_waitcnt lgkmcnt(0)
	v_mfma_f32_16x16x32_bf16 v[6:9], v[6:9], v[38:41], v[50:53]
	v_mfma_f32_16x16x32_bf16 v[2:5], v[42:45], v[38:41], v[2:5]
	v_rcp_f32_e32 v38, v35
	s_nop 0
	v_fma_f32 v39, -v35, v38, 1.0
	v_fmac_f32_e32 v38, v39, v38
	v_div_scale_f32 v39, vcc, 1.0, v34, 1.0
	v_mul_f32_e32 v40, v39, v38
	v_fma_f32 v41, -v35, v40, v39
	v_fmac_f32_e32 v40, v41, v38
	v_fma_f32 v35, -v35, v40, v39
	v_div_fmas_f32 v35, v35, v38, v40
	v_div_fixup_f32 v34, v35, v34, 1.0
	v_lshl_add_u64 v[38:39], v[36:37], 0, s[8:9]
	v_pk_mul_f32 v[30:31], v[30:31], v[34:35] op_sel_hi:[1,0]
	v_pk_mul_f32 v[32:33], v[32:33], v[34:35] op_sel_hi:[1,0]
	s_mov_b32 s8, 0x286c0000
	v_cvt_pk_bf16_f32 v30, v30, v31
	v_cvt_pk_bf16_f32 v31, v32, v33
	v_add_co_u32_e32 v32, vcc, s8, v36
	v_pk_mul_f32 v[26:27], v[26:27], v[34:35] op_sel_hi:[1,0]
	v_pk_mul_f32 v[28:29], v[28:29], v[34:35] op_sel_hi:[1,0]
	v_pk_mul_f32 v[22:23], v[22:23], v[34:35] op_sel_hi:[1,0]
	v_pk_mul_f32 v[24:25], v[24:25], v[34:35] op_sel_hi:[1,0]
	v_pk_mul_f32 v[18:19], v[18:19], v[34:35] op_sel_hi:[1,0]
	v_pk_mul_f32 v[20:21], v[20:21], v[34:35] op_sel_hi:[1,0]
	v_pk_mul_f32 v[14:15], v[14:15], v[34:35] op_sel_hi:[1,0]
	v_pk_mul_f32 v[16:17], v[16:17], v[34:35] op_sel_hi:[1,0]
	v_pk_mul_f32 v[10:11], v[10:11], v[34:35] op_sel_hi:[1,0]
	v_pk_mul_f32 v[12:13], v[12:13], v[34:35] op_sel_hi:[1,0]
	v_pk_mul_f32 v[6:7], v[6:7], v[34:35] op_sel_hi:[1,0]
	v_pk_mul_f32 v[8:9], v[8:9], v[34:35] op_sel_hi:[1,0]
	v_pk_mul_f32 v[2:3], v[2:3], v[34:35] op_sel_hi:[1,0]
	v_pk_mul_f32 v[4:5], v[4:5], v[34:35] op_sel_hi:[1,0]
	v_addc_co_u32_e32 v33, vcc, 0, v37, vcc
	v_cvt_pk_bf16_f32 v26, v26, v27
	v_cvt_pk_bf16_f32 v27, v28, v29
	v_cvt_pk_bf16_f32 v22, v22, v23
	v_cvt_pk_bf16_f32 v23, v24, v25
	v_cvt_pk_bf16_f32 v18, v18, v19
	v_cvt_pk_bf16_f32 v19, v20, v21
	v_cvt_pk_bf16_f32 v14, v14, v15
	v_cvt_pk_bf16_f32 v15, v16, v17
	v_cvt_pk_bf16_f32 v10, v10, v11
	v_cvt_pk_bf16_f32 v11, v12, v13
	v_cvt_pk_bf16_f32 v6, v6, v7
	v_cvt_pk_bf16_f32 v7, v8, v9
	v_cvt_pk_bf16_f32 v2, v2, v3
	v_cvt_pk_bf16_f32 v3, v4, v5
	global_store_dwordx2 v[32:33], v[30:31], off
	global_store_dwordx2 v[38:39], v[26:27], off offset:32
	global_store_dwordx2 v[38:39], v[22:23], off offset:64
	global_store_dwordx2 v[38:39], v[18:19], off offset:96
	global_store_dwordx2 v[38:39], v[14:15], off offset:128
	global_store_dwordx2 v[38:39], v[10:11], off offset:160
	global_store_dwordx2 v[38:39], v[6:7], off offset:192
	global_store_dwordx2 v[38:39], v[2:3], off offset:224
	s_barrier
	s_cbranch_scc0 .LBB0_1180
